# conversion inner loops fully unrolled: 32 loads in flight per item
# baseline (speedup 1.0000x reference)
; #define LAS __attribute__((address_space(3)))
; __device__ __forceinline__ void transpose_item(const float* W, int K, int N, bf16_t* WT, LAS float* scr, int item, int lane, int perm_cols) {
;     const int nblk = N / 32, kb = item / nblk, nb = item % nblk, k0 = 64 * kb, n0 = 32 * nb;
; #pragma unroll 8
;     for (int i = 0; i < 32; ++i) { const int kk = 2 * i + (lane >> 5); scr[kk * 33 + (lane & 31)] = W[(size_t)(k0 + kk) * N + n0 + (lane & 31)]; }
.LBB0_338:
	s_lshl_b32 s22, s19, 1
	s_lshl_b32 s21, s18, 1
	v_or_b32_e32 v176, s22, v14
	v_or_b32_e32 v22, s21, v5
	v_mov_b32_e32 v23, v177
	s_waitcnt vmcnt(7)
	v_lshlrev_b64 v[24:25], 13, v[176:177]
	v_lshlrev_b64 v[22:23], 13, v[22:23]
	v_lshl_add_u64 v[24:25], v[12:13], 0, v[24:25]
	v_lshl_add_u64 v[22:23], v[12:13], 0, v[22:23]
	global_load_dword v80, v[24:25], off
	global_load_dword v81, v[22:23], off
	v_or_b32_e32 v26, s21, v1
	v_or_b32_e32 v27, s22, v0
	v_mad_u64_u32 v[96:97], s[24:25], v27, s60, v[4:5]
	v_mad_u64_u32 v[98:99], s[24:25], v26, s60, v[4:5]
	s_add_i32 s24, s22, 4
	s_add_i32 s23, s21, 4
	v_or_b32_e32 v176, s24, v14
	v_mov_b32_e32 v23, v177
	v_or_b32_e32 v26, s23, v1
	v_or_b32_e32 v27, s24, v0
	s_add_i32 s19, s19, 16
	s_add_i32 s18, s18, 16
	s_add_i32 s20, s20, -16
	v_or_b32_e32 v22, s23, v5
	v_lshlrev_b64 v[24:25], 13, v[176:177]
	v_lshlrev_b64 v[22:23], 13, v[22:23]
	v_lshl_add_u64 v[24:25], v[12:13], 0, v[24:25]
	v_lshl_add_u64 v[22:23], v[12:13], 0, v[22:23]
	global_load_dword v82, v[24:25], off
	global_load_dword v83, v[22:23], off
	v_mad_u64_u32 v[100:101], s[24:25], v27, s60, v[4:5]
	v_mad_u64_u32 v[102:103], s[24:25], v26, s60, v[4:5]
	s_add_i32 s24, s22, 8
	s_add_i32 s23, s21, 8
	v_or_b32_e32 v176, s24, v14
	v_mov_b32_e32 v23, v177
	v_or_b32_e32 v26, s23, v1
	v_or_b32_e32 v27, s24, v0
	v_or_b32_e32 v22, s23, v5
	v_lshlrev_b64 v[24:25], 13, v[176:177]
	v_lshlrev_b64 v[22:23], 13, v[22:23]
	v_lshl_add_u64 v[24:25], v[12:13], 0, v[24:25]
	v_lshl_add_u64 v[22:23], v[12:13], 0, v[22:23]
	global_load_dword v84, v[24:25], off
	global_load_dword v85, v[22:23], off
	v_mad_u64_u32 v[104:105], s[24:25], v27, s60, v[4:5]
	v_mad_u64_u32 v[106:107], s[24:25], v26, s60, v[4:5]
	s_add_i32 s24, s22, 12
	s_add_i32 s23, s21, 12
	v_or_b32_e32 v176, s24, v14
	v_mov_b32_e32 v23, v177
	v_or_b32_e32 v26, s23, v1
	v_or_b32_e32 v27, s24, v0
	v_or_b32_e32 v22, s23, v5
	v_lshlrev_b64 v[24:25], 13, v[176:177]
	v_lshlrev_b64 v[22:23], 13, v[22:23]
	v_lshl_add_u64 v[24:25], v[12:13], 0, v[24:25]
	v_lshl_add_u64 v[22:23], v[12:13], 0, v[22:23]
	global_load_dword v86, v[24:25], off
	global_load_dword v87, v[22:23], off
	v_mad_u64_u32 v[108:109], s[24:25], v27, s60, v[4:5]
	v_mad_u64_u32 v[110:111], s[24:25], v26, s60, v[4:5]
	s_add_i32 s24, s22, 16
	s_add_i32 s23, s21, 16
	v_or_b32_e32 v176, s24, v14
	v_mov_b32_e32 v23, v177
	v_or_b32_e32 v26, s23, v1
	v_or_b32_e32 v27, s24, v0
	v_or_b32_e32 v22, s23, v5
	v_lshlrev_b64 v[24:25], 13, v[176:177]
	v_lshlrev_b64 v[22:23], 13, v[22:23]
	v_lshl_add_u64 v[24:25], v[12:13], 0, v[24:25]
	v_lshl_add_u64 v[22:23], v[12:13], 0, v[22:23]
	global_load_dword v88, v[24:25], off
	global_load_dword v89, v[22:23], off
	v_mad_u64_u32 v[112:113], s[24:25], v27, s60, v[4:5]
	v_mad_u64_u32 v[114:115], s[24:25], v26, s60, v[4:5]
	s_add_i32 s24, s22, 20
	s_add_i32 s23, s21, 20
	v_or_b32_e32 v176, s24, v14
	v_mov_b32_e32 v23, v177
	v_or_b32_e32 v26, s23, v1
	v_or_b32_e32 v27, s24, v0
	v_or_b32_e32 v22, s23, v5
	v_lshlrev_b64 v[24:25], 13, v[176:177]
	v_lshlrev_b64 v[22:23], 13, v[22:23]
	v_lshl_add_u64 v[24:25], v[12:13], 0, v[24:25]
	v_lshl_add_u64 v[22:23], v[12:13], 0, v[22:23]
	global_load_dword v90, v[24:25], off
	global_load_dword v91, v[22:23], off
	v_mad_u64_u32 v[116:117], s[24:25], v27, s60, v[4:5]
	v_mad_u64_u32 v[118:119], s[24:25], v26, s60, v[4:5]
	s_add_i32 s24, s22, 24
	s_add_i32 s23, s21, 24
	v_or_b32_e32 v176, s24, v14
	v_mov_b32_e32 v23, v177
	v_or_b32_e32 v26, s23, v1
	v_or_b32_e32 v27, s24, v0
	s_add_i32 s22, s22, 28
	s_add_i32 s21, s21, 28
	s_cmp_lg_u32 s20, 0
	v_or_b32_e32 v22, s23, v5
	v_lshlrev_b64 v[24:25], 13, v[176:177]
	v_lshlrev_b64 v[22:23], 13, v[22:23]
	v_lshl_add_u64 v[24:25], v[12:13], 0, v[24:25]
	v_lshl_add_u64 v[22:23], v[12:13], 0, v[22:23]
	global_load_dword v92, v[24:25], off
	global_load_dword v93, v[22:23], off
	v_mad_u64_u32 v[120:121], s[24:25], v27, s60, v[4:5]
	v_mad_u64_u32 v[122:123], s[24:25], v26, s60, v[4:5]
	v_or_b32_e32 v176, s22, v14
	v_mov_b32_e32 v23, v177
	v_or_b32_e32 v27, s22, v0
	v_or_b32_e32 v26, s21, v1
	v_or_b32_e32 v22, s21, v5
	v_lshlrev_b64 v[24:25], 13, v[176:177]
	v_lshlrev_b64 v[22:23], 13, v[22:23]
	v_lshl_add_u64 v[24:25], v[12:13], 0, v[24:25]
	v_lshl_add_u64 v[22:23], v[12:13], 0, v[22:23]
	global_load_dword v94, v[24:25], off
	global_load_dword v95, v[22:23], off
	v_mad_u64_u32 v[124:125], s[22:23], v27, s60, v[4:5]
	v_mad_u64_u32 v[126:127], s[22:23], v26, s60, v[4:5]
	s_lshl_b32 s22, s19, 1
	s_lshl_b32 s21, s18, 1
	v_or_b32_e32 v176, s22, v14
	v_or_b32_e32 v22, s21, v5
	v_mov_b32_e32 v23, v177
	v_lshlrev_b64 v[24:25], 13, v[176:177]
	v_lshlrev_b64 v[22:23], 13, v[22:23]
	v_lshl_add_u64 v[24:25], v[12:13], 0, v[24:25]
	v_lshl_add_u64 v[22:23], v[12:13], 0, v[22:23]
	global_load_dword v128, v[24:25], off
	global_load_dword v129, v[22:23], off
	v_or_b32_e32 v26, s21, v1
	v_or_b32_e32 v27, s22, v0
	v_mad_u64_u32 v[144:145], s[24:25], v27, s60, v[4:5]
	v_mad_u64_u32 v[146:147], s[24:25], v26, s60, v[4:5]
	s_add_i32 s24, s22, 4
	s_add_i32 s23, s21, 4
	v_or_b32_e32 v176, s24, v14
	v_mov_b32_e32 v23, v177
	v_or_b32_e32 v26, s23, v1
	v_or_b32_e32 v27, s24, v0
	s_add_i32 s19, s19, 16
	s_add_i32 s18, s18, 16
	s_add_i32 s20, s20, -16
	v_or_b32_e32 v22, s23, v5
	v_lshlrev_b64 v[24:25], 13, v[176:177]
	v_lshlrev_b64 v[22:23], 13, v[22:23]
	v_lshl_add_u64 v[24:25], v[12:13], 0, v[24:25]
	v_lshl_add_u64 v[22:23], v[12:13], 0, v[22:23]
	global_load_dword v130, v[24:25], off
	global_load_dword v131, v[22:23], off
	v_mad_u64_u32 v[148:149], s[24:25], v27, s60, v[4:5]
	v_mad_u64_u32 v[150:151], s[24:25], v26, s60, v[4:5]
	s_add_i32 s24, s22, 8
	s_add_i32 s23, s21, 8
; #define LAS __attribute__((address_space(3)))
; __device__ __forceinline__ unsigned pk2(float lo, float hi) { unsigned r; asm("v_cvt_pk_bf16_f32 %0, %1, %2" : "=v"(r) : "v"(lo), "v"(hi)); return r; }
; __device__ __forceinline__ void transpose_item(const float* W, int K, int N, bf16_t* WT, LAS float* scr, int item, int lane, int perm_cols) {
;     ...
;     for (int i = 0; i < 32; ++i) { const int kk = 2 * i + (lane >> 5); scr[kk * 33 + (lane & 31)] = W[(size_t)(k0 + kk) * N + n0 + (lane & 31)]; }
;     asm volatile("s_waitcnt lgkmcnt(0)" ::: "memory");
;     const int c = lane & 7;
; #pragma unroll
;     for (int j = 0; j < 4; ++j) { const int n = (lane >> 3) + 8 * j; const LAS float* s = scr + (8 * c) * 33 + n;
;         u32x4 o; o.x = pk2(s[0 * 33], s[1 * 33]); o.y = pk2(s[2 * 33], s[3 * 33]); o.z = pk2(s[4 * 33], s[5 * 33]); o.w = pk2(s[6 * 33], s[7 * 33]);
;         int rowi = n0 + n;
;         if (rowi < perm_cols) { const int oc = rowi & 255, part = oc >> 6, i6 = oc & 63; rowi = (rowi & ~255) + 128 * (part & 1) + 32 * (2 * (part >> 1) + (i6 >> 5)) + (i6 & 31); }
;         *(u32x4*)(WT + (size_t)rowi * K + k0 + 8 * c) = o; }
;     asm volatile("s_waitcnt lgkmcnt(0)" ::: "memory");
	v_or_b32_e32 v176, s24, v14
	v_mov_b32_e32 v23, v177
	v_or_b32_e32 v26, s23, v1
	v_or_b32_e32 v27, s24, v0
	v_or_b32_e32 v22, s23, v5
	v_lshlrev_b64 v[24:25], 13, v[176:177]
	v_lshlrev_b64 v[22:23], 13, v[22:23]
	v_lshl_add_u64 v[24:25], v[12:13], 0, v[24:25]
	v_lshl_add_u64 v[22:23], v[12:13], 0, v[22:23]
	global_load_dword v132, v[24:25], off
	global_load_dword v133, v[22:23], off
	v_mad_u64_u32 v[152:153], s[24:25], v27, s60, v[4:5]
	v_mad_u64_u32 v[154:155], s[24:25], v26, s60, v[4:5]
	s_add_i32 s24, s22, 12
	s_add_i32 s23, s21, 12
	v_or_b32_e32 v176, s24, v14
	v_mov_b32_e32 v23, v177
	v_or_b32_e32 v26, s23, v1
	v_or_b32_e32 v27, s24, v0
	v_or_b32_e32 v22, s23, v5
	v_lshlrev_b64 v[24:25], 13, v[176:177]
	v_lshlrev_b64 v[22:23], 13, v[22:23]
	v_lshl_add_u64 v[24:25], v[12:13], 0, v[24:25]
	v_lshl_add_u64 v[22:23], v[12:13], 0, v[22:23]
	global_load_dword v134, v[24:25], off
	global_load_dword v135, v[22:23], off
	v_mad_u64_u32 v[156:157], s[24:25], v27, s60, v[4:5]
	v_mad_u64_u32 v[158:159], s[24:25], v26, s60, v[4:5]
	s_add_i32 s24, s22, 16
	s_add_i32 s23, s21, 16
	v_or_b32_e32 v176, s24, v14
	v_mov_b32_e32 v23, v177
	v_or_b32_e32 v26, s23, v1
	v_or_b32_e32 v27, s24, v0
	v_or_b32_e32 v22, s23, v5
	v_lshlrev_b64 v[24:25], 13, v[176:177]
	v_lshlrev_b64 v[22:23], 13, v[22:23]
	v_lshl_add_u64 v[24:25], v[12:13], 0, v[24:25]
	v_lshl_add_u64 v[22:23], v[12:13], 0, v[22:23]
	global_load_dword v136, v[24:25], off
	global_load_dword v137, v[22:23], off
	v_mad_u64_u32 v[160:161], s[24:25], v27, s60, v[4:5]
	v_mad_u64_u32 v[162:163], s[24:25], v26, s60, v[4:5]
	s_add_i32 s24, s22, 20
	s_add_i32 s23, s21, 20
	v_or_b32_e32 v176, s24, v14
	v_mov_b32_e32 v23, v177
	v_or_b32_e32 v26, s23, v1
	v_or_b32_e32 v27, s24, v0
	v_or_b32_e32 v22, s23, v5
	v_lshlrev_b64 v[24:25], 13, v[176:177]
	v_lshlrev_b64 v[22:23], 13, v[22:23]
	v_lshl_add_u64 v[24:25], v[12:13], 0, v[24:25]
	v_lshl_add_u64 v[22:23], v[12:13], 0, v[22:23]
	global_load_dword v138, v[24:25], off
	global_load_dword v139, v[22:23], off
	v_mad_u64_u32 v[164:165], s[24:25], v27, s60, v[4:5]
	v_mad_u64_u32 v[166:167], s[24:25], v26, s60, v[4:5]
	s_add_i32 s24, s22, 24
	s_add_i32 s23, s21, 24
	v_or_b32_e32 v176, s24, v14
	v_mov_b32_e32 v23, v177
	v_or_b32_e32 v26, s23, v1
	v_or_b32_e32 v27, s24, v0
	s_add_i32 s22, s22, 28
	s_add_i32 s21, s21, 28
	s_cmp_lg_u32 s20, 0
	v_or_b32_e32 v22, s23, v5
	v_lshlrev_b64 v[24:25], 13, v[176:177]
	v_lshlrev_b64 v[22:23], 13, v[22:23]
	v_lshl_add_u64 v[24:25], v[12:13], 0, v[24:25]
	v_lshl_add_u64 v[22:23], v[12:13], 0, v[22:23]
	global_load_dword v140, v[24:25], off
	global_load_dword v141, v[22:23], off
	v_mad_u64_u32 v[168:169], s[24:25], v27, s60, v[4:5]
	v_mad_u64_u32 v[170:171], s[24:25], v26, s60, v[4:5]
	v_or_b32_e32 v176, s22, v14
	v_mov_b32_e32 v23, v177
	v_or_b32_e32 v27, s22, v0
	v_or_b32_e32 v26, s21, v1
	v_or_b32_e32 v22, s21, v5
	v_lshlrev_b64 v[24:25], 13, v[176:177]
	v_lshlrev_b64 v[22:23], 13, v[22:23]
	v_lshl_add_u64 v[24:25], v[12:13], 0, v[24:25]
	v_lshl_add_u64 v[22:23], v[12:13], 0, v[22:23]
	global_load_dword v142, v[24:25], off
	global_load_dword v143, v[22:23], off
	v_mad_u64_u32 v[172:173], s[22:23], v27, s60, v[4:5]
	v_mad_u64_u32 v[174:175], s[22:23], v26, s60, v[4:5]
	s_waitcnt vmcnt(31)
	ds_write_b32 v96, v80
	s_waitcnt vmcnt(30)
	ds_write_b32 v98, v81
	s_waitcnt vmcnt(29)
	ds_write_b32 v100, v82
	s_waitcnt vmcnt(28)
	ds_write_b32 v102, v83
	s_waitcnt vmcnt(27)
	ds_write_b32 v104, v84
	s_waitcnt vmcnt(26)
	ds_write_b32 v106, v85
	s_waitcnt vmcnt(25)
	ds_write_b32 v108, v86
	s_waitcnt vmcnt(24)
	ds_write_b32 v110, v87
	s_waitcnt vmcnt(23)
	ds_write_b32 v112, v88
	s_waitcnt vmcnt(22)
	ds_write_b32 v114, v89
	s_waitcnt vmcnt(21)
	ds_write_b32 v116, v90
	s_waitcnt vmcnt(20)
	ds_write_b32 v118, v91
	s_waitcnt vmcnt(19)
	ds_write_b32 v120, v92
	s_waitcnt vmcnt(18)
	ds_write_b32 v122, v93
	s_waitcnt vmcnt(17)
	ds_write_b32 v124, v94
	s_waitcnt vmcnt(16)
	ds_write_b32 v126, v95
	s_waitcnt vmcnt(15)
	ds_write_b32 v144, v128
	s_waitcnt vmcnt(14)
	ds_write_b32 v146, v129
	s_waitcnt vmcnt(13)
	ds_write_b32 v148, v130
	s_waitcnt vmcnt(12)
	ds_write_b32 v150, v131
	s_waitcnt vmcnt(11)
	ds_write_b32 v152, v132
	s_waitcnt vmcnt(10)
	ds_write_b32 v154, v133
	s_waitcnt vmcnt(9)
	ds_write_b32 v156, v134
	s_waitcnt vmcnt(8)
	ds_write_b32 v158, v135
	s_waitcnt vmcnt(7)
	ds_write_b32 v160, v136
	s_waitcnt vmcnt(6)
	ds_write_b32 v162, v137
	s_waitcnt vmcnt(5)
	ds_write_b32 v164, v138
	s_waitcnt vmcnt(4)
	ds_write_b32 v166, v139
	s_waitcnt vmcnt(3)
	ds_write_b32 v168, v140
	s_waitcnt vmcnt(2)
	ds_write_b32 v170, v141
	s_waitcnt vmcnt(1)
	ds_write_b32 v172, v142
	s_waitcnt vmcnt(0)
	ds_write_b32 v174, v143
	s_waitcnt lgkmcnt(0)
	ds_read2_b32 v[26:27], v18 offset0:33 offset1:41
	ds_read2_b32 v[28:29], v18 offset1:8
	ds_read2_b32 v[30:31], v18 offset0:66 offset1:74
	ds_read2_b32 v[32:33], v18 offset0:99 offset1:107
	ds_read2_b32 v[34:35], v18 offset0:132 offset1:140
	ds_read2_b32 v[36:37], v18 offset0:165 offset1:173
	ds_read2_b32 v[38:39], v18 offset0:198 offset1:206
	ds_read2_b32 v[40:41], v18 offset0:231 offset1:239
	s_lshl_b32 s72, s17, 1
	v_or_b32_e32 v5, s16, v17
	v_lshl_add_u64 v[12:13], v[6:7], 0, s[72:73]
	v_lshlrev_b32_e32 v176, 13, v5
	v_or_b32_e32 v5, s16, v19
	s_waitcnt lgkmcnt(6)
	v_cvt_pk_bf16_f32 v22, v28, v26
	v_lshl_add_u64 v[42:43], v[12:13], 0, v[176:177]
	v_lshlrev_b32_e32 v176, 13, v5
	s_waitcnt lgkmcnt(4)
	v_cvt_pk_bf16_f32 v23, v30, v32
	s_waitcnt lgkmcnt(2)
	v_cvt_pk_bf16_f32 v24, v34, v36
	s_waitcnt lgkmcnt(0)
	v_cvt_pk_bf16_f32 v25, v38, v40
	global_store_dwordx4 v[42:43], v[22:25], off
	v_or_b32_e32 v5, s16, v20
	s_nop 0
	v_cvt_pk_bf16_f32 v22, v29, v27
	v_lshl_add_u64 v[26:27], v[12:13], 0, v[176:177]
	v_cvt_pk_bf16_f32 v23, v31, v33
	v_cvt_pk_bf16_f32 v24, v35, v37
	v_cvt_pk_bf16_f32 v25, v39, v41
	global_store_dwordx4 v[26:27], v[22:25], off
	ds_read2_b32 v[26:27], v18 offset0:16 offset1:24
	ds_read2_b32 v[28:29], v18 offset0:49 offset1:57
	ds_read2_b32 v[30:31], v18 offset0:82 offset1:90
	ds_read2_b32 v[32:33], v18 offset0:115 offset1:123
	ds_read2_b32 v[34:35], v18 offset0:148 offset1:156
	ds_read2_b32 v[36:37], v18 offset0:181 offset1:189
	ds_read2_b32 v[38:39], v18 offset0:214 offset1:222
	ds_read2_b32 v[40:41], v18 offset0:247 offset1:255
	v_lshlrev_b32_e32 v176, 13, v5
	v_or_b32_e32 v5, s16, v21
	v_lshl_add_u64 v[42:43], v[12:13], 0, v[176:177]
	v_lshlrev_b32_e32 v176, 13, v5
	s_waitcnt lgkmcnt(6)
	v_cvt_pk_bf16_f32 v22, v26, v28
	s_waitcnt lgkmcnt(4)
	v_cvt_pk_bf16_f32 v23, v30, v32
	s_waitcnt lgkmcnt(2)
	v_cvt_pk_bf16_f32 v24, v34, v36
	s_waitcnt lgkmcnt(0)
	v_cvt_pk_bf16_f32 v25, v38, v40
	v_lshl_add_u64 v[12:13], v[12:13], 0, v[176:177]
	global_store_dwordx4 v[42:43], v[22:25], off
	s_nop 1
	v_cvt_pk_bf16_f32 v22, v27, v29
	v_cvt_pk_bf16_f32 v23, v31, v33
	v_cvt_pk_bf16_f32 v24, v35, v37
	v_cvt_pk_bf16_f32 v25, v39, v41
	global_store_dwordx4 v[12:13], v[22:25], off
	s_waitcnt lgkmcnt(0)
	s_branch .LBB0_334

; #define LAS __attribute__((address_space(3)))
; __device__ __forceinline__ void transpose_item(const float* W, int K, int N, bf16_t* WT, LAS float* scr, int item, int lane, int perm_cols) {
;     const int nblk = N / 32, kb = item / nblk, nb = item % nblk, k0 = 64 * kb, n0 = 32 * nb;
; #pragma unroll 8
;     for (int i = 0; i < 32; ++i) { const int kk = 2 * i + (lane >> 5); scr[kk * 33 + (lane & 31)] = W[(size_t)(k0 + kk) * N + n0 + (lane & 31)]; }
.LBB0_341:
	s_lshl_b32 s21, s18, 1
	s_lshl_b32 s20, s17, 1
	v_or_b32_e32 v22, s21, v14
	s_waitcnt vmcnt(7)
	v_or_b32_e32 v24, s20, v5
	v_mad_i64_i32 v[22:23], s[22:23], v22, s63, v[12:13]
	v_mad_i64_i32 v[24:25], s[22:23], v24, s63, v[12:13]
	global_load_dword v80, v[22:23], off
	global_load_dword v81, v[24:25], off
	v_or_b32_e32 v26, s20, v1
	v_or_b32_e32 v27, s21, v0
	v_mad_u64_u32 v[96:97], s[22:23], v27, s60, v[4:5]
	v_mad_u64_u32 v[98:99], s[22:23], v26, s60, v[4:5]
	s_add_i32 s23, s21, 4
	s_add_i32 s22, s20, 4
	v_or_b32_e32 v26, s22, v1
	v_or_b32_e32 v27, s23, v0
	s_add_i32 s18, s18, 16
	s_add_i32 s17, s17, 16
	s_add_i32 s19, s19, -16
	v_or_b32_e32 v22, s23, v14
	v_or_b32_e32 v24, s22, v5
	v_mad_i64_i32 v[22:23], s[22:23], v22, s63, v[12:13]
	v_mad_i64_i32 v[24:25], s[22:23], v24, s63, v[12:13]
	global_load_dword v82, v[22:23], off
	global_load_dword v83, v[24:25], off
	v_mad_u64_u32 v[100:101], s[22:23], v27, s60, v[4:5]
	v_mad_u64_u32 v[102:103], s[22:23], v26, s60, v[4:5]
	s_add_i32 s23, s21, 8
	s_add_i32 s22, s20, 8
	v_or_b32_e32 v26, s22, v1
	v_or_b32_e32 v27, s23, v0
	v_or_b32_e32 v22, s23, v14
	v_or_b32_e32 v24, s22, v5
	v_mad_i64_i32 v[22:23], s[22:23], v22, s63, v[12:13]
	v_mad_i64_i32 v[24:25], s[22:23], v24, s63, v[12:13]
	global_load_dword v84, v[22:23], off
	global_load_dword v85, v[24:25], off
	v_mad_u64_u32 v[104:105], s[22:23], v27, s60, v[4:5]
	v_mad_u64_u32 v[106:107], s[22:23], v26, s60, v[4:5]
	s_add_i32 s23, s21, 12
	s_add_i32 s22, s20, 12
	v_or_b32_e32 v26, s22, v1
	v_or_b32_e32 v27, s23, v0
	v_or_b32_e32 v22, s23, v14
	v_or_b32_e32 v24, s22, v5
	v_mad_i64_i32 v[22:23], s[22:23], v22, s63, v[12:13]
	v_mad_i64_i32 v[24:25], s[22:23], v24, s63, v[12:13]
	global_load_dword v86, v[22:23], off
	global_load_dword v87, v[24:25], off
	v_mad_u64_u32 v[108:109], s[22:23], v27, s60, v[4:5]
	v_mad_u64_u32 v[110:111], s[22:23], v26, s60, v[4:5]
	s_add_i32 s23, s21, 16
	s_add_i32 s22, s20, 16
	v_or_b32_e32 v26, s22, v1
	v_or_b32_e32 v27, s23, v0
	v_or_b32_e32 v22, s23, v14
	v_or_b32_e32 v24, s22, v5
	v_mad_i64_i32 v[22:23], s[22:23], v22, s63, v[12:13]
	v_mad_i64_i32 v[24:25], s[22:23], v24, s63, v[12:13]
	global_load_dword v88, v[22:23], off
	global_load_dword v89, v[24:25], off
	v_mad_u64_u32 v[112:113], s[22:23], v27, s60, v[4:5]
	v_mad_u64_u32 v[114:115], s[22:23], v26, s60, v[4:5]
	s_add_i32 s23, s21, 20
	s_add_i32 s22, s20, 20
	v_or_b32_e32 v26, s22, v1
	v_or_b32_e32 v27, s23, v0
	v_or_b32_e32 v22, s23, v14
	v_or_b32_e32 v24, s22, v5
	v_mad_i64_i32 v[22:23], s[22:23], v22, s63, v[12:13]
	v_mad_i64_i32 v[24:25], s[22:23], v24, s63, v[12:13]
	global_load_dword v90, v[22:23], off
	global_load_dword v91, v[24:25], off
	v_mad_u64_u32 v[116:117], s[22:23], v27, s60, v[4:5]
	v_mad_u64_u32 v[118:119], s[22:23], v26, s60, v[4:5]
	s_add_i32 s23, s21, 24
	s_add_i32 s22, s20, 24
	v_or_b32_e32 v26, s22, v1
	v_or_b32_e32 v27, s23, v0
	s_add_i32 s21, s21, 28
	s_add_i32 s20, s20, 28
	s_cmp_lg_u32 s19, 0
	v_or_b32_e32 v22, s23, v14
	v_or_b32_e32 v24, s22, v5
	v_mad_i64_i32 v[22:23], s[22:23], v22, s63, v[12:13]
	v_mad_i64_i32 v[24:25], s[22:23], v24, s63, v[12:13]
	global_load_dword v92, v[22:23], off
	global_load_dword v93, v[24:25], off
	v_mad_u64_u32 v[120:121], s[22:23], v27, s60, v[4:5]
	v_mad_u64_u32 v[122:123], s[22:23], v26, s60, v[4:5]
	v_or_b32_e32 v26, s20, v1
	v_or_b32_e32 v27, s21, v0
	v_or_b32_e32 v22, s21, v14
	v_or_b32_e32 v24, s20, v5
	v_mad_i64_i32 v[22:23], s[20:21], v22, s63, v[12:13]
	v_mad_i64_i32 v[24:25], s[20:21], v24, s63, v[12:13]
	global_load_dword v94, v[22:23], off
	global_load_dword v95, v[24:25], off
	v_mad_u64_u32 v[124:125], s[20:21], v27, s60, v[4:5]
	v_mad_u64_u32 v[126:127], s[20:21], v26, s60, v[4:5]
	s_lshl_b32 s21, s18, 1
	s_lshl_b32 s20, s17, 1
	v_or_b32_e32 v22, s21, v14
	v_or_b32_e32 v24, s20, v5
	v_mad_i64_i32 v[22:23], s[22:23], v22, s63, v[12:13]
	v_mad_i64_i32 v[24:25], s[22:23], v24, s63, v[12:13]
	global_load_dword v128, v[22:23], off
	global_load_dword v129, v[24:25], off
	v_or_b32_e32 v26, s20, v1
	v_or_b32_e32 v27, s21, v0
	v_mad_u64_u32 v[144:145], s[22:23], v27, s60, v[4:5]
	v_mad_u64_u32 v[146:147], s[22:23], v26, s60, v[4:5]
	s_add_i32 s23, s21, 4
	s_add_i32 s22, s20, 4
	v_or_b32_e32 v26, s22, v1
	v_or_b32_e32 v27, s23, v0
	s_add_i32 s18, s18, 16
	s_add_i32 s17, s17, 16
	s_add_i32 s19, s19, -16
	v_or_b32_e32 v22, s23, v14
	v_or_b32_e32 v24, s22, v5
	v_mad_i64_i32 v[22:23], s[22:23], v22, s63, v[12:13]
	v_mad_i64_i32 v[24:25], s[22:23], v24, s63, v[12:13]
	global_load_dword v130, v[22:23], off
	global_load_dword v131, v[24:25], off
	v_mad_u64_u32 v[148:149], s[22:23], v27, s60, v[4:5]
	v_mad_u64_u32 v[150:151], s[22:23], v26, s60, v[4:5]
	s_add_i32 s23, s21, 8
	s_add_i32 s22, s20, 8
	v_or_b32_e32 v26, s22, v1
	v_or_b32_e32 v27, s23, v0
	v_or_b32_e32 v22, s23, v14
	v_or_b32_e32 v24, s22, v5
	v_mad_i64_i32 v[22:23], s[22:23], v22, s63, v[12:13]
	v_mad_i64_i32 v[24:25], s[22:23], v24, s63, v[12:13]
	global_load_dword v132, v[22:23], off
	global_load_dword v133, v[24:25], off
	v_mad_u64_u32 v[152:153], s[22:23], v27, s60, v[4:5]
	v_mad_u64_u32 v[154:155], s[22:23], v26, s60, v[4:5]
	s_add_i32 s23, s21, 12
	s_add_i32 s22, s20, 12
	v_or_b32_e32 v26, s22, v1
	v_or_b32_e32 v27, s23, v0
	v_or_b32_e32 v22, s23, v14
	v_or_b32_e32 v24, s22, v5
	v_mad_i64_i32 v[22:23], s[22:23], v22, s63, v[12:13]
	v_mad_i64_i32 v[24:25], s[22:23], v24, s63, v[12:13]
	global_load_dword v134, v[22:23], off
	global_load_dword v135, v[24:25], off
	v_mad_u64_u32 v[156:157], s[22:23], v27, s60, v[4:5]
	v_mad_u64_u32 v[158:159], s[22:23], v26, s60, v[4:5]
	s_add_i32 s23, s21, 16
	s_add_i32 s22, s20, 16
; #define LAS __attribute__((address_space(3)))
; __device__ __forceinline__ unsigned pk2(float lo, float hi) { unsigned r; asm("v_cvt_pk_bf16_f32 %0, %1, %2" : "=v"(r) : "v"(lo), "v"(hi)); return r; }
; __device__ __forceinline__ void transpose_item(const float* W, int K, int N, bf16_t* WT, LAS float* scr, int item, int lane, int perm_cols) {
;     ...
;     for (int i = 0; i < 32; ++i) { const int kk = 2 * i + (lane >> 5); scr[kk * 33 + (lane & 31)] = W[(size_t)(k0 + kk) * N + n0 + (lane & 31)]; }
;     asm volatile("s_waitcnt lgkmcnt(0)" ::: "memory");
;     const int c = lane & 7;
; #pragma unroll
;     for (int j = 0; j < 4; ++j) { const int n = (lane >> 3) + 8 * j; const LAS float* s = scr + (8 * c) * 33 + n;
;         u32x4 o; o.x = pk2(s[0 * 33], s[1 * 33]); o.y = pk2(s[2 * 33], s[3 * 33]); o.z = pk2(s[4 * 33], s[5 * 33]); o.w = pk2(s[6 * 33], s[7 * 33]);
;         int rowi = n0 + n;
;         if (rowi < perm_cols) { const int oc = rowi & 255, part = oc >> 6, i6 = oc & 63; rowi = (rowi & ~255) + 128 * (part & 1) + 32 * (2 * (part >> 1) + (i6 >> 5)) + (i6 & 31); }
;         *(u32x4*)(WT + (size_t)rowi * K + k0 + 8 * c) = o; }
;     asm volatile("s_waitcnt lgkmcnt(0)" ::: "memory");
	v_or_b32_e32 v26, s22, v1
	v_or_b32_e32 v27, s23, v0
	v_or_b32_e32 v22, s23, v14
	v_or_b32_e32 v24, s22, v5
	v_mad_i64_i32 v[22:23], s[22:23], v22, s63, v[12:13]
	v_mad_i64_i32 v[24:25], s[22:23], v24, s63, v[12:13]
	global_load_dword v136, v[22:23], off
	global_load_dword v137, v[24:25], off
	v_mad_u64_u32 v[160:161], s[22:23], v27, s60, v[4:5]
	v_mad_u64_u32 v[162:163], s[22:23], v26, s60, v[4:5]
	s_add_i32 s23, s21, 20
	s_add_i32 s22, s20, 20
	v_or_b32_e32 v26, s22, v1
	v_or_b32_e32 v27, s23, v0
	v_or_b32_e32 v22, s23, v14
	v_or_b32_e32 v24, s22, v5
	v_mad_i64_i32 v[22:23], s[22:23], v22, s63, v[12:13]
	v_mad_i64_i32 v[24:25], s[22:23], v24, s63, v[12:13]
	global_load_dword v138, v[22:23], off
	global_load_dword v139, v[24:25], off
	v_mad_u64_u32 v[164:165], s[22:23], v27, s60, v[4:5]
	v_mad_u64_u32 v[166:167], s[22:23], v26, s60, v[4:5]
	s_add_i32 s23, s21, 24
	s_add_i32 s22, s20, 24
	v_or_b32_e32 v26, s22, v1
	v_or_b32_e32 v27, s23, v0
	s_add_i32 s21, s21, 28
	s_add_i32 s20, s20, 28
	s_cmp_lg_u32 s19, 0
	v_or_b32_e32 v22, s23, v14
	v_or_b32_e32 v24, s22, v5
	v_mad_i64_i32 v[22:23], s[22:23], v22, s63, v[12:13]
	v_mad_i64_i32 v[24:25], s[22:23], v24, s63, v[12:13]
	global_load_dword v140, v[22:23], off
	global_load_dword v141, v[24:25], off
	v_mad_u64_u32 v[168:169], s[22:23], v27, s60, v[4:5]
	v_mad_u64_u32 v[170:171], s[22:23], v26, s60, v[4:5]
	v_or_b32_e32 v26, s20, v1
	v_or_b32_e32 v27, s21, v0
	v_or_b32_e32 v22, s21, v14
	v_or_b32_e32 v24, s20, v5
	v_mad_i64_i32 v[22:23], s[20:21], v22, s63, v[12:13]
	v_mad_i64_i32 v[24:25], s[20:21], v24, s63, v[12:13]
	global_load_dword v142, v[22:23], off
	global_load_dword v143, v[24:25], off
	v_mad_u64_u32 v[172:173], s[20:21], v27, s60, v[4:5]
	v_mad_u64_u32 v[174:175], s[20:21], v26, s60, v[4:5]
	s_waitcnt vmcnt(31)
	ds_write_b32 v96, v80
	s_waitcnt vmcnt(30)
	ds_write_b32 v98, v81
	s_waitcnt vmcnt(29)
	ds_write_b32 v100, v82
	s_waitcnt vmcnt(28)
	ds_write_b32 v102, v83
	s_waitcnt vmcnt(27)
	ds_write_b32 v104, v84
	s_waitcnt vmcnt(26)
	ds_write_b32 v106, v85
	s_waitcnt vmcnt(25)
	ds_write_b32 v108, v86
	s_waitcnt vmcnt(24)
	ds_write_b32 v110, v87
	s_waitcnt vmcnt(23)
	ds_write_b32 v112, v88
	s_waitcnt vmcnt(22)
	ds_write_b32 v114, v89
	s_waitcnt vmcnt(21)
	ds_write_b32 v116, v90
	s_waitcnt vmcnt(20)
	ds_write_b32 v118, v91
	s_waitcnt vmcnt(19)
	ds_write_b32 v120, v92
	s_waitcnt vmcnt(18)
	ds_write_b32 v122, v93
	s_waitcnt vmcnt(17)
	ds_write_b32 v124, v94
	s_waitcnt vmcnt(16)
	ds_write_b32 v126, v95
	s_waitcnt vmcnt(15)
	ds_write_b32 v144, v128
	s_waitcnt vmcnt(14)
	ds_write_b32 v146, v129
	s_waitcnt vmcnt(13)
	ds_write_b32 v148, v130
	s_waitcnt vmcnt(12)
	ds_write_b32 v150, v131
	s_waitcnt vmcnt(11)
	ds_write_b32 v152, v132
	s_waitcnt vmcnt(10)
	ds_write_b32 v154, v133
	s_waitcnt vmcnt(9)
	ds_write_b32 v156, v134
	s_waitcnt vmcnt(8)
	ds_write_b32 v158, v135
	s_waitcnt vmcnt(7)
	ds_write_b32 v160, v136
	s_waitcnt vmcnt(6)
	ds_write_b32 v162, v137
	s_waitcnt vmcnt(5)
	ds_write_b32 v164, v138
	s_waitcnt vmcnt(4)
	ds_write_b32 v166, v139
	s_waitcnt vmcnt(3)
	ds_write_b32 v168, v140
	s_waitcnt vmcnt(2)
	ds_write_b32 v170, v141
	s_waitcnt vmcnt(1)
	ds_write_b32 v172, v142
	s_waitcnt vmcnt(0)
	ds_write_b32 v174, v143
	s_lshl_b32 s16, s16, 6
	s_and_b32 s16, s16, 0x80
	s_lshr_b32 s17, s40, 1
	s_and_b32 s18, s40, 0xffffff20
	s_waitcnt lgkmcnt(0)
	s_and_b32 s17, s17, 64
	s_or_b32 s16, s18, s16
	s_or_b32 s16, s16, s17
	ds_read2_b32 v[26:27], v18 offset0:33 offset1:41
	ds_read2_b32 v[28:29], v18 offset1:8
	v_or_b32_e32 v5, s40, v17
	ds_read2_b32 v[30:31], v18 offset0:66 offset1:74
	ds_read2_b32 v[32:33], v18 offset0:99 offset1:107
	ds_read2_b32 v[34:35], v18 offset0:132 offset1:140
	ds_read2_b32 v[36:37], v18 offset0:165 offset1:173
	ds_read2_b32 v[38:39], v18 offset0:198 offset1:206
	ds_read2_b32 v[40:41], v18 offset0:231 offset1:239
	v_cmp_gt_i32_e32 vcc, s47, v5
	v_or_b32_e32 v14, s16, v17
	s_ashr_i32 s45, s44, 31
	v_cndmask_b32_e32 v42, v5, v14, vcc
	v_ashrrev_i32_e32 v43, 31, v42
	v_or_b32_e32 v5, s40, v19
	v_lshl_add_u64 v[12:13], s[44:45], 1, v[10:11]
	v_lshlrev_b64 v[42:43], 12, v[42:43]
	v_cmp_gt_i32_e32 vcc, s47, v5
	v_or_b32_e32 v14, s16, v19
	s_waitcnt lgkmcnt(6)
	v_cvt_pk_bf16_f32 v22, v28, v26
	v_lshl_add_u64 v[42:43], v[12:13], 0, v[42:43]
	v_cndmask_b32_e32 v26, v5, v14, vcc
	s_waitcnt lgkmcnt(4)
	v_cvt_pk_bf16_f32 v23, v30, v32
	s_waitcnt lgkmcnt(2)
	v_cvt_pk_bf16_f32 v24, v34, v36
	s_waitcnt lgkmcnt(0)
	v_cvt_pk_bf16_f32 v25, v38, v40
	global_store_dwordx4 v[42:43], v[22:25], off
	v_or_b32_e32 v5, s40, v20
	v_cmp_gt_i32_e32 vcc, s47, v5
	v_cvt_pk_bf16_f32 v22, v29, v27
	v_ashrrev_i32_e32 v27, 31, v26
	v_lshlrev_b64 v[26:27], 12, v[26:27]
	v_lshl_add_u64 v[26:27], v[12:13], 0, v[26:27]
	v_cvt_pk_bf16_f32 v23, v31, v33
	v_cvt_pk_bf16_f32 v24, v35, v37
	v_cvt_pk_bf16_f32 v25, v39, v41
	global_store_dwordx4 v[26:27], v[22:25], off
	ds_read2_b32 v[26:27], v18 offset0:16 offset1:24
	ds_read2_b32 v[28:29], v18 offset0:49 offset1:57
	ds_read2_b32 v[30:31], v18 offset0:82 offset1:90
	ds_read2_b32 v[32:33], v18 offset0:115 offset1:123
	ds_read2_b32 v[34:35], v18 offset0:148 offset1:156
	ds_read2_b32 v[36:37], v18 offset0:181 offset1:189
	ds_read2_b32 v[38:39], v18 offset0:214 offset1:222
	ds_read2_b32 v[40:41], v18 offset0:247 offset1:255
	v_or_b32_e32 v14, s16, v20
	v_cndmask_b32_e32 v42, v5, v14, vcc
	v_ashrrev_i32_e32 v43, 31, v42
	v_or_b32_e32 v5, s40, v21
	v_lshlrev_b64 v[42:43], 12, v[42:43]
	v_cmp_gt_i32_e32 vcc, s47, v5
	v_or_b32_e32 v14, s16, v21
	s_waitcnt lgkmcnt(6)
	v_cvt_pk_bf16_f32 v22, v26, v28
	v_lshl_add_u64 v[42:43], v[12:13], 0, v[42:43]
	v_cndmask_b32_e32 v26, v5, v14, vcc
	s_waitcnt lgkmcnt(4)
	v_cvt_pk_bf16_f32 v23, v30, v32
	s_waitcnt lgkmcnt(2)
	v_cvt_pk_bf16_f32 v24, v34, v36
	s_waitcnt lgkmcnt(0)
	v_cvt_pk_bf16_f32 v25, v38, v40
	global_store_dwordx4 v[42:43], v[22:25], off
	s_nop 1
	v_cvt_pk_bf16_f32 v22, v27, v29
	v_ashrrev_i32_e32 v27, 31, v26
	v_lshlrev_b64 v[26:27], 12, v[26:27]
	v_lshl_add_u64 v[12:13], v[12:13], 0, v[26:27]
	v_cvt_pk_bf16_f32 v23, v31, v33
	v_cvt_pk_bf16_f32 v24, v35, v37
	v_cvt_pk_bf16_f32 v25, v39, v41
	global_store_dwordx4 v[12:13], v[22:25], off
	s_waitcnt lgkmcnt(0)
	s_branch .LBB0_334

; #define LAS __attribute__((address_space(3)))
; __device__ __forceinline__ void transpose_item(const float* W, int K, int N, bf16_t* WT, LAS float* scr, int item, int lane, int perm_cols) {
;     const int nblk = N / 32, kb = item / nblk, nb = item % nblk, k0 = 64 * kb, n0 = 32 * nb;
; #pragma unroll 8
;     for (int i = 0; i < 32; ++i) { const int kk = 2 * i + (lane >> 5); scr[kk * 33 + (lane & 31)] = W[(size_t)(k0 + kk) * N + n0 + (lane & 31)]; }
.LBB0_351:
	s_lshl_b32 s20, s17, 1
	s_lshl_b32 s19, s16, 1
	v_or_b32_e32 v176, s20, v14
	s_waitcnt vmcnt(8)
	v_or_b32_e32 v20, s19, v5
	v_mov_b32_e32 v21, v177
	v_lshlrev_b64 v[22:23], 13, v[176:177]
	v_lshlrev_b64 v[20:21], 13, v[20:21]
	v_lshl_add_u64 v[22:23], v[12:13], 0, v[22:23]
	v_lshl_add_u64 v[20:21], v[12:13], 0, v[20:21]
	global_load_dword v80, v[22:23], off
	global_load_dword v81, v[20:21], off
	s_waitcnt vmcnt(9)
	v_or_b32_e32 v24, s19, v1
	v_or_b32_e32 v25, s20, v0
	v_mad_u64_u32 v[96:97], s[22:23], v25, s60, v[4:5]
	v_mad_u64_u32 v[98:99], s[22:23], v24, s60, v[4:5]
	s_add_i32 s22, s20, 4
	s_add_i32 s21, s19, 4
	v_or_b32_e32 v176, s22, v14
	v_mov_b32_e32 v21, v177
	v_or_b32_e32 v24, s21, v1
	v_or_b32_e32 v25, s22, v0
	s_add_i32 s17, s17, 16
	s_add_i32 s16, s16, 16
	s_add_i32 s18, s18, -16
	v_or_b32_e32 v20, s21, v5
	v_lshlrev_b64 v[22:23], 13, v[176:177]
	v_lshlrev_b64 v[20:21], 13, v[20:21]
	v_lshl_add_u64 v[22:23], v[12:13], 0, v[22:23]
	v_lshl_add_u64 v[20:21], v[12:13], 0, v[20:21]
	global_load_dword v82, v[22:23], off
	global_load_dword v83, v[20:21], off
	v_mad_u64_u32 v[100:101], s[22:23], v25, s60, v[4:5]
	v_mad_u64_u32 v[102:103], s[22:23], v24, s60, v[4:5]
	s_add_i32 s22, s20, 8
	s_add_i32 s21, s19, 8
	v_or_b32_e32 v176, s22, v14
	v_mov_b32_e32 v21, v177
	v_or_b32_e32 v24, s21, v1
	v_or_b32_e32 v25, s22, v0
	v_or_b32_e32 v20, s21, v5
	v_lshlrev_b64 v[22:23], 13, v[176:177]
	v_lshlrev_b64 v[20:21], 13, v[20:21]
	v_lshl_add_u64 v[22:23], v[12:13], 0, v[22:23]
	v_lshl_add_u64 v[20:21], v[12:13], 0, v[20:21]
	global_load_dword v84, v[22:23], off
	global_load_dword v85, v[20:21], off
	v_mad_u64_u32 v[104:105], s[22:23], v25, s60, v[4:5]
	v_mad_u64_u32 v[106:107], s[22:23], v24, s60, v[4:5]
	s_add_i32 s22, s20, 12
	s_add_i32 s21, s19, 12
	v_or_b32_e32 v176, s22, v14
	v_mov_b32_e32 v21, v177
	v_or_b32_e32 v24, s21, v1
	v_or_b32_e32 v25, s22, v0
	v_or_b32_e32 v20, s21, v5
	v_lshlrev_b64 v[22:23], 13, v[176:177]
	v_lshlrev_b64 v[20:21], 13, v[20:21]
	v_lshl_add_u64 v[22:23], v[12:13], 0, v[22:23]
	v_lshl_add_u64 v[20:21], v[12:13], 0, v[20:21]
	global_load_dword v86, v[22:23], off
	global_load_dword v87, v[20:21], off
	v_mad_u64_u32 v[108:109], s[22:23], v25, s60, v[4:5]
	v_mad_u64_u32 v[110:111], s[22:23], v24, s60, v[4:5]
	s_add_i32 s22, s20, 16
	s_add_i32 s21, s19, 16
	v_or_b32_e32 v176, s22, v14
	v_mov_b32_e32 v21, v177
	v_or_b32_e32 v24, s21, v1
	v_or_b32_e32 v25, s22, v0
	v_or_b32_e32 v20, s21, v5
	v_lshlrev_b64 v[22:23], 13, v[176:177]
	v_lshlrev_b64 v[20:21], 13, v[20:21]
	v_lshl_add_u64 v[22:23], v[12:13], 0, v[22:23]
	v_lshl_add_u64 v[20:21], v[12:13], 0, v[20:21]
	global_load_dword v88, v[22:23], off
	global_load_dword v89, v[20:21], off
	v_mad_u64_u32 v[112:113], s[22:23], v25, s60, v[4:5]
	v_mad_u64_u32 v[114:115], s[22:23], v24, s60, v[4:5]
	s_add_i32 s22, s20, 20
	s_add_i32 s21, s19, 20
	v_or_b32_e32 v176, s22, v14
	v_mov_b32_e32 v21, v177
	v_or_b32_e32 v24, s21, v1
	v_or_b32_e32 v25, s22, v0
	v_or_b32_e32 v20, s21, v5
	v_lshlrev_b64 v[22:23], 13, v[176:177]
	v_lshlrev_b64 v[20:21], 13, v[20:21]
	v_lshl_add_u64 v[22:23], v[12:13], 0, v[22:23]
	v_lshl_add_u64 v[20:21], v[12:13], 0, v[20:21]
	global_load_dword v90, v[22:23], off
	global_load_dword v91, v[20:21], off
	v_mad_u64_u32 v[116:117], s[22:23], v25, s60, v[4:5]
	v_mad_u64_u32 v[118:119], s[22:23], v24, s60, v[4:5]
	s_add_i32 s22, s20, 24
	s_add_i32 s21, s19, 24
	v_or_b32_e32 v176, s22, v14
	v_mov_b32_e32 v21, v177
	v_or_b32_e32 v24, s21, v1
	v_or_b32_e32 v25, s22, v0
	s_add_i32 s20, s20, 28
	s_add_i32 s19, s19, 28
	s_cmp_lg_u32 s18, 0
	v_or_b32_e32 v20, s21, v5
	v_lshlrev_b64 v[22:23], 13, v[176:177]
	v_lshlrev_b64 v[20:21], 13, v[20:21]
	v_lshl_add_u64 v[22:23], v[12:13], 0, v[22:23]
	v_lshl_add_u64 v[20:21], v[12:13], 0, v[20:21]
	global_load_dword v92, v[22:23], off
	global_load_dword v93, v[20:21], off
	v_mad_u64_u32 v[120:121], s[22:23], v25, s60, v[4:5]
	v_mad_u64_u32 v[122:123], s[22:23], v24, s60, v[4:5]
	v_or_b32_e32 v176, s20, v14
	v_mov_b32_e32 v21, v177
	v_or_b32_e32 v25, s20, v0
	v_or_b32_e32 v24, s19, v1
	v_or_b32_e32 v20, s19, v5
	v_lshlrev_b64 v[22:23], 13, v[176:177]
	v_lshlrev_b64 v[20:21], 13, v[20:21]
	v_lshl_add_u64 v[22:23], v[12:13], 0, v[22:23]
	v_lshl_add_u64 v[20:21], v[12:13], 0, v[20:21]
	global_load_dword v94, v[22:23], off
	global_load_dword v95, v[20:21], off
	v_mad_u64_u32 v[124:125], s[20:21], v25, s60, v[4:5]
	v_mad_u64_u32 v[126:127], s[20:21], v24, s60, v[4:5]
	s_lshl_b32 s20, s17, 1
	s_lshl_b32 s19, s16, 1
	v_or_b32_e32 v176, s20, v14
	v_or_b32_e32 v20, s19, v5
	v_mov_b32_e32 v21, v177
	v_lshlrev_b64 v[22:23], 13, v[176:177]
	v_lshlrev_b64 v[20:21], 13, v[20:21]
	v_lshl_add_u64 v[22:23], v[12:13], 0, v[22:23]
	v_lshl_add_u64 v[20:21], v[12:13], 0, v[20:21]
	global_load_dword v128, v[22:23], off
	global_load_dword v129, v[20:21], off
	v_or_b32_e32 v24, s19, v1
	v_or_b32_e32 v25, s20, v0
	v_mad_u64_u32 v[144:145], s[22:23], v25, s60, v[4:5]
	v_mad_u64_u32 v[146:147], s[22:23], v24, s60, v[4:5]
	s_add_i32 s22, s20, 4
	s_add_i32 s21, s19, 4
	v_or_b32_e32 v176, s22, v14
	v_mov_b32_e32 v21, v177
	v_or_b32_e32 v24, s21, v1
	v_or_b32_e32 v25, s22, v0
	s_add_i32 s17, s17, 16
	s_add_i32 s16, s16, 16
	s_add_i32 s18, s18, -16
	v_or_b32_e32 v20, s21, v5
	v_lshlrev_b64 v[22:23], 13, v[176:177]
	v_lshlrev_b64 v[20:21], 13, v[20:21]
	v_lshl_add_u64 v[22:23], v[12:13], 0, v[22:23]
	v_lshl_add_u64 v[20:21], v[12:13], 0, v[20:21]
	global_load_dword v130, v[22:23], off
	global_load_dword v131, v[20:21], off
	v_mad_u64_u32 v[148:149], s[22:23], v25, s60, v[4:5]
	v_mad_u64_u32 v[150:151], s[22:23], v24, s60, v[4:5]
	s_add_i32 s22, s20, 8
; #define LAS __attribute__((address_space(3)))
; __device__ __forceinline__ unsigned pk2(float lo, float hi) { unsigned r; asm("v_cvt_pk_bf16_f32 %0, %1, %2" : "=v"(r) : "v"(lo), "v"(hi)); return r; }
; __device__ __forceinline__ void transpose_item(const float* W, int K, int N, bf16_t* WT, LAS float* scr, int item, int lane, int perm_cols) {
;     ...
;     for (int i = 0; i < 32; ++i) { const int kk = 2 * i + (lane >> 5); scr[kk * 33 + (lane & 31)] = W[(size_t)(k0 + kk) * N + n0 + (lane & 31)]; }
;     asm volatile("s_waitcnt lgkmcnt(0)" ::: "memory");
;     const int c = lane & 7;
; #pragma unroll
;     for (int j = 0; j < 4; ++j) { const int n = (lane >> 3) + 8 * j; const LAS float* s = scr + (8 * c) * 33 + n;
;         u32x4 o; o.x = pk2(s[0 * 33], s[1 * 33]); o.y = pk2(s[2 * 33], s[3 * 33]); o.z = pk2(s[4 * 33], s[5 * 33]); o.w = pk2(s[6 * 33], s[7 * 33]);
;         int rowi = n0 + n;
;         if (rowi < perm_cols) { const int oc = rowi & 255, part = oc >> 6, i6 = oc & 63; rowi = (rowi & ~255) + 128 * (part & 1) + 32 * (2 * (part >> 1) + (i6 >> 5)) + (i6 & 31); }
;         *(u32x4*)(WT + (size_t)rowi * K + k0 + 8 * c) = o; }
;     asm volatile("s_waitcnt lgkmcnt(0)" ::: "memory");
	s_add_i32 s21, s19, 8
	v_or_b32_e32 v176, s22, v14
	v_mov_b32_e32 v21, v177
	v_or_b32_e32 v24, s21, v1
	v_or_b32_e32 v25, s22, v0
	v_or_b32_e32 v20, s21, v5
	v_lshlrev_b64 v[22:23], 13, v[176:177]
	v_lshlrev_b64 v[20:21], 13, v[20:21]
	v_lshl_add_u64 v[22:23], v[12:13], 0, v[22:23]
	v_lshl_add_u64 v[20:21], v[12:13], 0, v[20:21]
	global_load_dword v132, v[22:23], off
	global_load_dword v133, v[20:21], off
	v_mad_u64_u32 v[152:153], s[22:23], v25, s60, v[4:5]
	v_mad_u64_u32 v[154:155], s[22:23], v24, s60, v[4:5]
	s_add_i32 s22, s20, 12
	s_add_i32 s21, s19, 12
	v_or_b32_e32 v176, s22, v14
	v_mov_b32_e32 v21, v177
	v_or_b32_e32 v24, s21, v1
	v_or_b32_e32 v25, s22, v0
	v_or_b32_e32 v20, s21, v5
	v_lshlrev_b64 v[22:23], 13, v[176:177]
	v_lshlrev_b64 v[20:21], 13, v[20:21]
	v_lshl_add_u64 v[22:23], v[12:13], 0, v[22:23]
	v_lshl_add_u64 v[20:21], v[12:13], 0, v[20:21]
	global_load_dword v134, v[22:23], off
	global_load_dword v135, v[20:21], off
	v_mad_u64_u32 v[156:157], s[22:23], v25, s60, v[4:5]
	v_mad_u64_u32 v[158:159], s[22:23], v24, s60, v[4:5]
	s_add_i32 s22, s20, 16
	s_add_i32 s21, s19, 16
	v_or_b32_e32 v176, s22, v14
	v_mov_b32_e32 v21, v177
	v_or_b32_e32 v24, s21, v1
	v_or_b32_e32 v25, s22, v0
	v_or_b32_e32 v20, s21, v5
	v_lshlrev_b64 v[22:23], 13, v[176:177]
	v_lshlrev_b64 v[20:21], 13, v[20:21]
	v_lshl_add_u64 v[22:23], v[12:13], 0, v[22:23]
	v_lshl_add_u64 v[20:21], v[12:13], 0, v[20:21]
	global_load_dword v136, v[22:23], off
	global_load_dword v137, v[20:21], off
	v_mad_u64_u32 v[160:161], s[22:23], v25, s60, v[4:5]
	v_mad_u64_u32 v[162:163], s[22:23], v24, s60, v[4:5]
	s_add_i32 s22, s20, 20
	s_add_i32 s21, s19, 20
	v_or_b32_e32 v176, s22, v14
	v_mov_b32_e32 v21, v177
	v_or_b32_e32 v24, s21, v1
	v_or_b32_e32 v25, s22, v0
	v_or_b32_e32 v20, s21, v5
	v_lshlrev_b64 v[22:23], 13, v[176:177]
	v_lshlrev_b64 v[20:21], 13, v[20:21]
	v_lshl_add_u64 v[22:23], v[12:13], 0, v[22:23]
	v_lshl_add_u64 v[20:21], v[12:13], 0, v[20:21]
	global_load_dword v138, v[22:23], off
	global_load_dword v139, v[20:21], off
	v_mad_u64_u32 v[164:165], s[22:23], v25, s60, v[4:5]
	v_mad_u64_u32 v[166:167], s[22:23], v24, s60, v[4:5]
	s_add_i32 s22, s20, 24
	s_add_i32 s21, s19, 24
	v_or_b32_e32 v176, s22, v14
	v_mov_b32_e32 v21, v177
	v_or_b32_e32 v24, s21, v1
	v_or_b32_e32 v25, s22, v0
	s_add_i32 s20, s20, 28
	s_add_i32 s19, s19, 28
	s_cmp_lg_u32 s18, 0
	v_or_b32_e32 v20, s21, v5
	v_lshlrev_b64 v[22:23], 13, v[176:177]
	v_lshlrev_b64 v[20:21], 13, v[20:21]
	v_lshl_add_u64 v[22:23], v[12:13], 0, v[22:23]
	v_lshl_add_u64 v[20:21], v[12:13], 0, v[20:21]
	global_load_dword v140, v[22:23], off
	global_load_dword v141, v[20:21], off
	v_mad_u64_u32 v[168:169], s[22:23], v25, s60, v[4:5]
	v_mad_u64_u32 v[170:171], s[22:23], v24, s60, v[4:5]
	v_or_b32_e32 v176, s20, v14
	v_mov_b32_e32 v21, v177
	v_or_b32_e32 v25, s20, v0
	v_or_b32_e32 v24, s19, v1
	v_or_b32_e32 v20, s19, v5
	v_lshlrev_b64 v[22:23], 13, v[176:177]
	v_lshlrev_b64 v[20:21], 13, v[20:21]
	v_lshl_add_u64 v[22:23], v[12:13], 0, v[22:23]
	v_lshl_add_u64 v[20:21], v[12:13], 0, v[20:21]
	global_load_dword v142, v[22:23], off
	global_load_dword v143, v[20:21], off
	v_mad_u64_u32 v[172:173], s[20:21], v25, s60, v[4:5]
	v_mad_u64_u32 v[174:175], s[20:21], v24, s60, v[4:5]
	s_waitcnt vmcnt(31)
	ds_write_b32 v96, v80
	s_waitcnt vmcnt(30)
	ds_write_b32 v98, v81
	s_waitcnt vmcnt(29)
	ds_write_b32 v100, v82
	s_waitcnt vmcnt(28)
	ds_write_b32 v102, v83
	s_waitcnt vmcnt(27)
	ds_write_b32 v104, v84
	s_waitcnt vmcnt(26)
	ds_write_b32 v106, v85
	s_waitcnt vmcnt(25)
	ds_write_b32 v108, v86
	s_waitcnt vmcnt(24)
	ds_write_b32 v110, v87
	s_waitcnt vmcnt(23)
	ds_write_b32 v112, v88
	s_waitcnt vmcnt(22)
	ds_write_b32 v114, v89
	s_waitcnt vmcnt(21)
	ds_write_b32 v116, v90
	s_waitcnt vmcnt(20)
	ds_write_b32 v118, v91
	s_waitcnt vmcnt(19)
	ds_write_b32 v120, v92
	s_waitcnt vmcnt(18)
	ds_write_b32 v122, v93
	s_waitcnt vmcnt(17)
	ds_write_b32 v124, v94
	s_waitcnt vmcnt(16)
	ds_write_b32 v126, v95
	s_waitcnt vmcnt(15)
	ds_write_b32 v144, v128
	s_waitcnt vmcnt(14)
	ds_write_b32 v146, v129
	s_waitcnt vmcnt(13)
	ds_write_b32 v148, v130
	s_waitcnt vmcnt(12)
	ds_write_b32 v150, v131
	s_waitcnt vmcnt(11)
	ds_write_b32 v152, v132
	s_waitcnt vmcnt(10)
	ds_write_b32 v154, v133
	s_waitcnt vmcnt(9)
	ds_write_b32 v156, v134
	s_waitcnt vmcnt(8)
	ds_write_b32 v158, v135
	s_waitcnt vmcnt(7)
	ds_write_b32 v160, v136
	s_waitcnt vmcnt(6)
	ds_write_b32 v162, v137
	s_waitcnt vmcnt(5)
	ds_write_b32 v164, v138
	s_waitcnt vmcnt(4)
	ds_write_b32 v166, v139
	s_waitcnt vmcnt(3)
	ds_write_b32 v168, v140
	s_waitcnt vmcnt(2)
	ds_write_b32 v170, v141
	s_waitcnt vmcnt(1)
	ds_write_b32 v172, v142
	s_waitcnt vmcnt(0)
	ds_write_b32 v174, v143
	s_waitcnt lgkmcnt(0)
	ds_read2_b32 v[24:25], v15 offset0:33 offset1:41
	ds_read2_b32 v[26:27], v15 offset1:8
	ds_read2_b32 v[28:29], v15 offset0:66 offset1:74
	ds_read2_b32 v[30:31], v15 offset0:99 offset1:107
	ds_read2_b32 v[32:33], v15 offset0:132 offset1:140
	ds_read2_b32 v[34:35], v15 offset0:165 offset1:173
	ds_read2_b32 v[36:37], v15 offset0:198 offset1:206
	ds_read2_b32 v[38:39], v15 offset0:231 offset1:239
	s_lshl_b32 s72, s15, 1
	v_or_b32_e32 v5, s14, v16
	v_lshl_add_u64 v[12:13], v[6:7], 0, s[72:73]
	v_lshlrev_b32_e32 v176, 12, v5
	v_or_b32_e32 v5, s14, v17
	s_waitcnt lgkmcnt(6)
	v_cvt_pk_bf16_f32 v20, v26, v24
	v_lshl_add_u64 v[40:41], v[12:13], 0, v[176:177]
	v_lshlrev_b32_e32 v176, 12, v5
	s_waitcnt lgkmcnt(4)
	v_cvt_pk_bf16_f32 v21, v28, v30
	s_waitcnt lgkmcnt(2)
	v_cvt_pk_bf16_f32 v22, v32, v34
	s_waitcnt lgkmcnt(0)
	v_cvt_pk_bf16_f32 v23, v36, v38
	global_store_dwordx4 v[40:41], v[20:23], off
	v_or_b32_e32 v5, s14, v18
	s_nop 0
	v_cvt_pk_bf16_f32 v20, v27, v25
	v_lshl_add_u64 v[24:25], v[12:13], 0, v[176:177]
	v_cvt_pk_bf16_f32 v21, v29, v31
	v_cvt_pk_bf16_f32 v22, v33, v35
	v_cvt_pk_bf16_f32 v23, v37, v39
	global_store_dwordx4 v[24:25], v[20:23], off
	ds_read2_b32 v[24:25], v15 offset0:16 offset1:24
	ds_read2_b32 v[26:27], v15 offset0:49 offset1:57
	ds_read2_b32 v[28:29], v15 offset0:82 offset1:90
	ds_read2_b32 v[30:31], v15 offset0:115 offset1:123
	ds_read2_b32 v[32:33], v15 offset0:148 offset1:156
	ds_read2_b32 v[34:35], v15 offset0:181 offset1:189
	ds_read2_b32 v[36:37], v15 offset0:214 offset1:222
	ds_read2_b32 v[38:39], v15 offset0:247 offset1:255
	v_lshlrev_b32_e32 v176, 12, v5
	v_or_b32_e32 v5, s14, v19
	v_lshl_add_u64 v[40:41], v[12:13], 0, v[176:177]
	v_lshlrev_b32_e32 v176, 12, v5
	s_waitcnt lgkmcnt(6)
	v_cvt_pk_bf16_f32 v20, v24, v26
	s_waitcnt lgkmcnt(4)
	v_cvt_pk_bf16_f32 v21, v28, v30
	s_waitcnt lgkmcnt(2)
	v_cvt_pk_bf16_f32 v22, v32, v34
	s_waitcnt lgkmcnt(0)
	v_cvt_pk_bf16_f32 v23, v36, v38
	v_lshl_add_u64 v[12:13], v[12:13], 0, v[176:177]
	global_store_dwordx4 v[40:41], v[20:23], off
	s_nop 1
	v_cvt_pk_bf16_f32 v20, v25, v27
	v_cvt_pk_bf16_f32 v21, v29, v31
	v_cvt_pk_bf16_f32 v22, v33, v35
	v_cvt_pk_bf16_f32 v23, v37, v39
	global_store_dwordx4 v[12:13], v[20:23], off
	s_waitcnt lgkmcnt(0)
	s_branch .LBB0_347

; #define LAS __attribute__((address_space(3)))
; __device__ __forceinline__ void transpose_item(const float* W, int K, int N, bf16_t* WT, LAS float* scr, int item, int lane, int perm_cols) {
;     const int nblk = N / 32, kb = item / nblk, nb = item % nblk, k0 = 64 * kb, n0 = 32 * nb;
; #pragma unroll 8
;     for (int i = 0; i < 32; ++i) { const int kk = 2 * i + (lane >> 5); scr[kk * 33 + (lane & 31)] = W[(size_t)(k0 + kk) * N + n0 + (lane & 31)]; }
.LBB0_354:
	s_lshl_b32 s19, s16, 1
	s_lshl_b32 s18, s15, 1
	s_waitcnt vmcnt(8)
	v_or_b32_e32 v20, s19, v14
	v_or_b32_e32 v22, s18, v5
	v_mad_i64_i32 v[20:21], s[20:21], v20, s12, v[12:13]
	v_mad_i64_i32 v[22:23], s[20:21], v22, s12, v[12:13]
	global_load_dword v80, v[20:21], off
	global_load_dword v81, v[22:23], off
	s_waitcnt vmcnt(9)
	v_or_b32_e32 v24, s18, v1
	v_or_b32_e32 v25, s19, v0
	v_mad_u64_u32 v[96:97], s[20:21], v25, s60, v[4:5]
	v_mad_u64_u32 v[98:99], s[20:21], v24, s60, v[4:5]
	s_add_i32 s21, s19, 4
	s_add_i32 s20, s18, 4
	v_or_b32_e32 v24, s20, v1
	v_or_b32_e32 v25, s21, v0
	s_add_i32 s16, s16, 16
	s_add_i32 s15, s15, 16
	s_add_i32 s17, s17, -16
	v_or_b32_e32 v20, s21, v14
	v_or_b32_e32 v22, s20, v5
	v_mad_i64_i32 v[20:21], s[20:21], v20, s12, v[12:13]
	v_mad_i64_i32 v[22:23], s[20:21], v22, s12, v[12:13]
	global_load_dword v82, v[20:21], off
	global_load_dword v83, v[22:23], off
	v_mad_u64_u32 v[100:101], s[20:21], v25, s60, v[4:5]
	v_mad_u64_u32 v[102:103], s[20:21], v24, s60, v[4:5]
	s_add_i32 s21, s19, 8
	s_add_i32 s20, s18, 8
	v_or_b32_e32 v24, s20, v1
	v_or_b32_e32 v25, s21, v0
	v_or_b32_e32 v20, s21, v14
	v_or_b32_e32 v22, s20, v5
	v_mad_i64_i32 v[20:21], s[20:21], v20, s12, v[12:13]
	v_mad_i64_i32 v[22:23], s[20:21], v22, s12, v[12:13]
	global_load_dword v84, v[20:21], off
	global_load_dword v85, v[22:23], off
	v_mad_u64_u32 v[104:105], s[20:21], v25, s60, v[4:5]
	v_mad_u64_u32 v[106:107], s[20:21], v24, s60, v[4:5]
	s_add_i32 s21, s19, 12
	s_add_i32 s20, s18, 12
	v_or_b32_e32 v24, s20, v1
	v_or_b32_e32 v25, s21, v0
	v_or_b32_e32 v20, s21, v14
	v_or_b32_e32 v22, s20, v5
	v_mad_i64_i32 v[20:21], s[20:21], v20, s12, v[12:13]
	v_mad_i64_i32 v[22:23], s[20:21], v22, s12, v[12:13]
	global_load_dword v86, v[20:21], off
	global_load_dword v87, v[22:23], off
	v_mad_u64_u32 v[108:109], s[20:21], v25, s60, v[4:5]
	v_mad_u64_u32 v[110:111], s[20:21], v24, s60, v[4:5]
	s_add_i32 s21, s19, 16
	s_add_i32 s20, s18, 16
	v_or_b32_e32 v24, s20, v1
	v_or_b32_e32 v25, s21, v0
	v_or_b32_e32 v20, s21, v14
	v_or_b32_e32 v22, s20, v5
	v_mad_i64_i32 v[20:21], s[20:21], v20, s12, v[12:13]
	v_mad_i64_i32 v[22:23], s[20:21], v22, s12, v[12:13]
	global_load_dword v88, v[20:21], off
	global_load_dword v89, v[22:23], off
	v_mad_u64_u32 v[112:113], s[20:21], v25, s60, v[4:5]
	v_mad_u64_u32 v[114:115], s[20:21], v24, s60, v[4:5]
	s_add_i32 s21, s19, 20
	s_add_i32 s20, s18, 20
	v_or_b32_e32 v24, s20, v1
	v_or_b32_e32 v25, s21, v0
	v_or_b32_e32 v20, s21, v14
	v_or_b32_e32 v22, s20, v5
	v_mad_i64_i32 v[20:21], s[20:21], v20, s12, v[12:13]
	v_mad_i64_i32 v[22:23], s[20:21], v22, s12, v[12:13]
	global_load_dword v90, v[20:21], off
	global_load_dword v91, v[22:23], off
	v_mad_u64_u32 v[116:117], s[20:21], v25, s60, v[4:5]
	v_mad_u64_u32 v[118:119], s[20:21], v24, s60, v[4:5]
	s_add_i32 s21, s19, 24
	s_add_i32 s20, s18, 24
	v_or_b32_e32 v24, s20, v1
	v_or_b32_e32 v25, s21, v0
	s_add_i32 s19, s19, 28
	s_add_i32 s18, s18, 28
	s_cmp_lg_u32 s17, 0
	v_or_b32_e32 v20, s21, v14
	v_or_b32_e32 v22, s20, v5
	v_mad_i64_i32 v[20:21], s[20:21], v20, s12, v[12:13]
	v_mad_i64_i32 v[22:23], s[20:21], v22, s12, v[12:13]
	global_load_dword v92, v[20:21], off
	global_load_dword v93, v[22:23], off
	v_mad_u64_u32 v[120:121], s[20:21], v25, s60, v[4:5]
	v_mad_u64_u32 v[122:123], s[20:21], v24, s60, v[4:5]
	v_or_b32_e32 v24, s18, v1
	v_or_b32_e32 v25, s19, v0
	v_or_b32_e32 v20, s19, v14
	v_or_b32_e32 v22, s18, v5
	v_mad_i64_i32 v[20:21], s[18:19], v20, s12, v[12:13]
	v_mad_i64_i32 v[22:23], s[18:19], v22, s12, v[12:13]
	global_load_dword v94, v[20:21], off
	global_load_dword v95, v[22:23], off
	v_mad_u64_u32 v[124:125], s[18:19], v25, s60, v[4:5]
	v_mad_u64_u32 v[126:127], s[18:19], v24, s60, v[4:5]
	s_lshl_b32 s19, s16, 1
	s_lshl_b32 s18, s15, 1
	v_or_b32_e32 v20, s19, v14
	v_or_b32_e32 v22, s18, v5
	v_mad_i64_i32 v[20:21], s[20:21], v20, s12, v[12:13]
	v_mad_i64_i32 v[22:23], s[20:21], v22, s12, v[12:13]
	global_load_dword v128, v[20:21], off
	global_load_dword v129, v[22:23], off
	v_or_b32_e32 v24, s18, v1
	v_or_b32_e32 v25, s19, v0
	v_mad_u64_u32 v[144:145], s[20:21], v25, s60, v[4:5]
	v_mad_u64_u32 v[146:147], s[20:21], v24, s60, v[4:5]
	s_add_i32 s21, s19, 4
	s_add_i32 s20, s18, 4
	v_or_b32_e32 v24, s20, v1
	v_or_b32_e32 v25, s21, v0
	s_add_i32 s16, s16, 16
	s_add_i32 s15, s15, 16
	s_add_i32 s17, s17, -16
	v_or_b32_e32 v20, s21, v14
	v_or_b32_e32 v22, s20, v5
	v_mad_i64_i32 v[20:21], s[20:21], v20, s12, v[12:13]
	v_mad_i64_i32 v[22:23], s[20:21], v22, s12, v[12:13]
	global_load_dword v130, v[20:21], off
	global_load_dword v131, v[22:23], off
	v_mad_u64_u32 v[148:149], s[20:21], v25, s60, v[4:5]
	v_mad_u64_u32 v[150:151], s[20:21], v24, s60, v[4:5]
	s_add_i32 s21, s19, 8
	s_add_i32 s20, s18, 8
	v_or_b32_e32 v24, s20, v1
	v_or_b32_e32 v25, s21, v0
	v_or_b32_e32 v20, s21, v14
	v_or_b32_e32 v22, s20, v5
	v_mad_i64_i32 v[20:21], s[20:21], v20, s12, v[12:13]
	v_mad_i64_i32 v[22:23], s[20:21], v22, s12, v[12:13]
	global_load_dword v132, v[20:21], off
	global_load_dword v133, v[22:23], off
	v_mad_u64_u32 v[152:153], s[20:21], v25, s60, v[4:5]
	v_mad_u64_u32 v[154:155], s[20:21], v24, s60, v[4:5]
	s_add_i32 s21, s19, 12
	s_add_i32 s20, s18, 12
	v_or_b32_e32 v24, s20, v1
	v_or_b32_e32 v25, s21, v0
	v_or_b32_e32 v20, s21, v14
	v_or_b32_e32 v22, s20, v5
	v_mad_i64_i32 v[20:21], s[20:21], v20, s12, v[12:13]
	v_mad_i64_i32 v[22:23], s[20:21], v22, s12, v[12:13]
	global_load_dword v134, v[20:21], off
	global_load_dword v135, v[22:23], off
	v_mad_u64_u32 v[156:157], s[20:21], v25, s60, v[4:5]
	v_mad_u64_u32 v[158:159], s[20:21], v24, s60, v[4:5]
	s_add_i32 s21, s19, 16
	s_add_i32 s20, s18, 16
; #define LAS __attribute__((address_space(3)))
; __device__ __forceinline__ unsigned pk2(float lo, float hi) { unsigned r; asm("v_cvt_pk_bf16_f32 %0, %1, %2" : "=v"(r) : "v"(lo), "v"(hi)); return r; }
; __device__ __forceinline__ void transpose_item(const float* W, int K, int N, bf16_t* WT, LAS float* scr, int item, int lane, int perm_cols) {
;     ...
;     for (int i = 0; i < 32; ++i) { const int kk = 2 * i + (lane >> 5); scr[kk * 33 + (lane & 31)] = W[(size_t)(k0 + kk) * N + n0 + (lane & 31)]; }
;     asm volatile("s_waitcnt lgkmcnt(0)" ::: "memory");
;     const int c = lane & 7;
; #pragma unroll
;     for (int j = 0; j < 4; ++j) { const int n = (lane >> 3) + 8 * j; const LAS float* s = scr + (8 * c) * 33 + n;
;         u32x4 o; o.x = pk2(s[0 * 33], s[1 * 33]); o.y = pk2(s[2 * 33], s[3 * 33]); o.z = pk2(s[4 * 33], s[5 * 33]); o.w = pk2(s[6 * 33], s[7 * 33]);
;         int rowi = n0 + n;
;         if (rowi < perm_cols) { const int oc = rowi & 255, part = oc >> 6, i6 = oc & 63; rowi = (rowi & ~255) + 128 * (part & 1) + 32 * (2 * (part >> 1) + (i6 >> 5)) + (i6 & 31); }
;         *(u32x4*)(WT + (size_t)rowi * K + k0 + 8 * c) = o; }
;     asm volatile("s_waitcnt lgkmcnt(0)" ::: "memory");
	v_or_b32_e32 v24, s20, v1
	v_or_b32_e32 v25, s21, v0
	v_or_b32_e32 v20, s21, v14
	v_or_b32_e32 v22, s20, v5
	v_mad_i64_i32 v[20:21], s[20:21], v20, s12, v[12:13]
	v_mad_i64_i32 v[22:23], s[20:21], v22, s12, v[12:13]
	global_load_dword v136, v[20:21], off
	global_load_dword v137, v[22:23], off
	v_mad_u64_u32 v[160:161], s[20:21], v25, s60, v[4:5]
	v_mad_u64_u32 v[162:163], s[20:21], v24, s60, v[4:5]
	s_add_i32 s21, s19, 20
	s_add_i32 s20, s18, 20
	v_or_b32_e32 v24, s20, v1
	v_or_b32_e32 v25, s21, v0
	v_or_b32_e32 v20, s21, v14
	v_or_b32_e32 v22, s20, v5
	v_mad_i64_i32 v[20:21], s[20:21], v20, s12, v[12:13]
	v_mad_i64_i32 v[22:23], s[20:21], v22, s12, v[12:13]
	global_load_dword v138, v[20:21], off
	global_load_dword v139, v[22:23], off
	v_mad_u64_u32 v[164:165], s[20:21], v25, s60, v[4:5]
	v_mad_u64_u32 v[166:167], s[20:21], v24, s60, v[4:5]
	s_add_i32 s21, s19, 24
	s_add_i32 s20, s18, 24
	v_or_b32_e32 v24, s20, v1
	v_or_b32_e32 v25, s21, v0
	s_add_i32 s19, s19, 28
	s_add_i32 s18, s18, 28
	s_cmp_lg_u32 s17, 0
	v_or_b32_e32 v20, s21, v14
	v_or_b32_e32 v22, s20, v5
	v_mad_i64_i32 v[20:21], s[20:21], v20, s12, v[12:13]
	v_mad_i64_i32 v[22:23], s[20:21], v22, s12, v[12:13]
	global_load_dword v140, v[20:21], off
	global_load_dword v141, v[22:23], off
	v_mad_u64_u32 v[168:169], s[20:21], v25, s60, v[4:5]
	v_mad_u64_u32 v[170:171], s[20:21], v24, s60, v[4:5]
	v_or_b32_e32 v24, s18, v1
	v_or_b32_e32 v25, s19, v0
	v_or_b32_e32 v20, s19, v14
	v_or_b32_e32 v22, s18, v5
	v_mad_i64_i32 v[20:21], s[18:19], v20, s12, v[12:13]
	v_mad_i64_i32 v[22:23], s[18:19], v22, s12, v[12:13]
	global_load_dword v142, v[20:21], off
	global_load_dword v143, v[22:23], off
	v_mad_u64_u32 v[172:173], s[18:19], v25, s60, v[4:5]
	v_mad_u64_u32 v[174:175], s[18:19], v24, s60, v[4:5]
	s_waitcnt vmcnt(31)
	ds_write_b32 v96, v80
	s_waitcnt vmcnt(30)
	ds_write_b32 v98, v81
	s_waitcnt vmcnt(29)
	ds_write_b32 v100, v82
	s_waitcnt vmcnt(28)
	ds_write_b32 v102, v83
	s_waitcnt vmcnt(27)
	ds_write_b32 v104, v84
	s_waitcnt vmcnt(26)
	ds_write_b32 v106, v85
	s_waitcnt vmcnt(25)
	ds_write_b32 v108, v86
	s_waitcnt vmcnt(24)
	ds_write_b32 v110, v87
	s_waitcnt vmcnt(23)
	ds_write_b32 v112, v88
	s_waitcnt vmcnt(22)
	ds_write_b32 v114, v89
	s_waitcnt vmcnt(21)
	ds_write_b32 v116, v90
	s_waitcnt vmcnt(20)
	ds_write_b32 v118, v91
	s_waitcnt vmcnt(19)
	ds_write_b32 v120, v92
	s_waitcnt vmcnt(18)
	ds_write_b32 v122, v93
	s_waitcnt vmcnt(17)
	ds_write_b32 v124, v94
	s_waitcnt vmcnt(16)
	ds_write_b32 v126, v95
	s_waitcnt vmcnt(15)
	ds_write_b32 v144, v128
	s_waitcnt vmcnt(14)
	ds_write_b32 v146, v129
	s_waitcnt vmcnt(13)
	ds_write_b32 v148, v130
	s_waitcnt vmcnt(12)
	ds_write_b32 v150, v131
	s_waitcnt vmcnt(11)
	ds_write_b32 v152, v132
	s_waitcnt vmcnt(10)
	ds_write_b32 v154, v133
	s_waitcnt vmcnt(9)
	ds_write_b32 v156, v134
	s_waitcnt vmcnt(8)
	ds_write_b32 v158, v135
	s_waitcnt vmcnt(7)
	ds_write_b32 v160, v136
	s_waitcnt vmcnt(6)
	ds_write_b32 v162, v137
	s_waitcnt vmcnt(5)
	ds_write_b32 v164, v138
	s_waitcnt vmcnt(4)
	ds_write_b32 v166, v139
	s_waitcnt vmcnt(3)
	ds_write_b32 v168, v140
	s_waitcnt vmcnt(2)
	ds_write_b32 v170, v141
	s_waitcnt vmcnt(1)
	ds_write_b32 v172, v142
	s_waitcnt vmcnt(0)
	ds_write_b32 v174, v143
	s_lshl_b32 s15, s14, 6
	s_and_b32 s15, s15, 0x80
	s_lshr_b32 s16, s36, 1
	s_and_b32 s17, s36, 0xffffff20
	s_and_b32 s16, s16, 64
	s_or_b32 s15, s17, s15
	s_waitcnt lgkmcnt(0)
	s_or_b32 s15, s15, s16
	s_ashr_i32 s39, s38, 31
	ds_read2_b32 v[24:25], v15 offset0:33 offset1:41
	ds_read2_b32 v[26:27], v15 offset1:8
	s_cmp_lt_i32 s14, 0
	ds_read2_b32 v[28:29], v15 offset0:66 offset1:74
	ds_read2_b32 v[30:31], v15 offset0:99 offset1:107
	ds_read2_b32 v[32:33], v15 offset0:132 offset1:140
	ds_read2_b32 v[34:35], v15 offset0:165 offset1:173
	ds_read2_b32 v[36:37], v15 offset0:198 offset1:206
	ds_read2_b32 v[38:39], v15 offset0:231 offset1:239
	s_cselect_b32 s14, s15, s36
	v_or_b32_e32 v40, s14, v16
	v_ashrrev_i32_e32 v41, 31, v40
	v_lshl_add_u64 v[12:13], s[38:39], 1, v[10:11]
	v_lshlrev_b64 v[40:41], 12, v[40:41]
	s_waitcnt lgkmcnt(6)
	v_cvt_pk_bf16_f32 v20, v26, v24
	v_lshl_add_u64 v[40:41], v[12:13], 0, v[40:41]
	v_or_b32_e32 v24, s14, v17
	s_waitcnt lgkmcnt(4)
	v_cvt_pk_bf16_f32 v21, v28, v30
	s_waitcnt lgkmcnt(2)
	v_cvt_pk_bf16_f32 v22, v32, v34
	s_waitcnt lgkmcnt(0)
	v_cvt_pk_bf16_f32 v23, v36, v38
	global_store_dwordx4 v[40:41], v[20:23], off
	v_or_b32_e32 v40, s14, v18
	v_ashrrev_i32_e32 v41, 31, v40
	v_cvt_pk_bf16_f32 v20, v27, v25
	v_ashrrev_i32_e32 v25, 31, v24
	v_lshlrev_b64 v[24:25], 12, v[24:25]
	v_lshl_add_u64 v[24:25], v[12:13], 0, v[24:25]
	v_cvt_pk_bf16_f32 v21, v29, v31
	v_cvt_pk_bf16_f32 v22, v33, v35
	v_cvt_pk_bf16_f32 v23, v37, v39
	global_store_dwordx4 v[24:25], v[20:23], off
	ds_read2_b32 v[24:25], v15 offset0:16 offset1:24
	ds_read2_b32 v[26:27], v15 offset0:49 offset1:57
	ds_read2_b32 v[28:29], v15 offset0:82 offset1:90
	ds_read2_b32 v[30:31], v15 offset0:115 offset1:123
	ds_read2_b32 v[32:33], v15 offset0:148 offset1:156
	ds_read2_b32 v[34:35], v15 offset0:181 offset1:189
	ds_read2_b32 v[36:37], v15 offset0:214 offset1:222
	ds_read2_b32 v[38:39], v15 offset0:247 offset1:255
	v_lshlrev_b64 v[40:41], 12, v[40:41]
	s_waitcnt lgkmcnt(6)
	v_cvt_pk_bf16_f32 v20, v24, v26
	v_lshl_add_u64 v[40:41], v[12:13], 0, v[40:41]
	v_or_b32_e32 v24, s14, v19
	s_waitcnt lgkmcnt(4)
	v_cvt_pk_bf16_f32 v21, v28, v30
	s_waitcnt lgkmcnt(2)
	v_cvt_pk_bf16_f32 v22, v32, v34
	s_waitcnt lgkmcnt(0)
	v_cvt_pk_bf16_f32 v23, v36, v38
	global_store_dwordx4 v[40:41], v[20:23], off
	s_nop 1
	v_cvt_pk_bf16_f32 v20, v25, v27
	v_ashrrev_i32_e32 v25, 31, v24
	v_lshlrev_b64 v[24:25], 12, v[24:25]
	v_lshl_add_u64 v[12:13], v[12:13], 0, v[24:25]
	v_cvt_pk_bf16_f32 v21, v29, v31
	v_cvt_pk_bf16_f32 v22, v33, v35
	v_cvt_pk_bf16_f32 v23, v37, v39
	global_store_dwordx4 v[12:13], v[20:23], off
	s_waitcnt lgkmcnt(0)
	s_branch .LBB0_347

; #define LAS __attribute__((address_space(3)))
; __device__ __forceinline__ void transpose_item(const float* W, int K, int N, bf16_t* WT, LAS float* scr, int item, int lane, int perm_cols) {
;     const int nblk = N / 32, kb = item / nblk, nb = item % nblk, k0 = 64 * kb, n0 = 32 * nb;
; #pragma unroll 8
;     for (int i = 0; i < 32; ++i) { const int kk = 2 * i + (lane >> 5); scr[kk * 33 + (lane & 31)] = W[(size_t)(k0 + kk) * N + n0 + (lane & 31)]; }
.LBB0_583:
	s_lshl_b32 s22, s19, 1
	s_lshl_b32 s21, s18, 1
	v_or_b32_e32 v176, s22, v14
	v_or_b32_e32 v22, s21, v5
	v_mov_b32_e32 v23, v177
	v_lshlrev_b64 v[24:25], 13, v[176:177]
	v_lshlrev_b64 v[22:23], 13, v[22:23]
	v_lshl_add_u64 v[24:25], v[12:13], 0, v[24:25]
	v_lshl_add_u64 v[22:23], v[12:13], 0, v[22:23]
	global_load_dword v80, v[24:25], off
	global_load_dword v81, v[22:23], off
	v_or_b32_e32 v26, s21, v1
	v_or_b32_e32 v27, s22, v0
	v_mad_u64_u32 v[96:97], s[24:25], v27, s60, v[4:5]
	v_mad_u64_u32 v[98:99], s[24:25], v26, s60, v[4:5]
	s_add_i32 s24, s22, 4
	s_add_i32 s23, s21, 4
	v_or_b32_e32 v176, s24, v14
	v_mov_b32_e32 v23, v177
	v_or_b32_e32 v26, s23, v1
	v_or_b32_e32 v27, s24, v0
	s_add_i32 s19, s19, 16
	s_add_i32 s18, s18, 16
	s_add_i32 s20, s20, -16
	v_or_b32_e32 v22, s23, v5
	v_lshlrev_b64 v[24:25], 13, v[176:177]
	v_lshlrev_b64 v[22:23], 13, v[22:23]
	v_lshl_add_u64 v[24:25], v[12:13], 0, v[24:25]
	v_lshl_add_u64 v[22:23], v[12:13], 0, v[22:23]
	global_load_dword v82, v[24:25], off
	global_load_dword v83, v[22:23], off
	v_mad_u64_u32 v[100:101], s[24:25], v27, s60, v[4:5]
	v_mad_u64_u32 v[102:103], s[24:25], v26, s60, v[4:5]
	s_add_i32 s24, s22, 8
	s_add_i32 s23, s21, 8
	v_or_b32_e32 v176, s24, v14
	v_mov_b32_e32 v23, v177
	v_or_b32_e32 v26, s23, v1
	v_or_b32_e32 v27, s24, v0
	v_or_b32_e32 v22, s23, v5
	v_lshlrev_b64 v[24:25], 13, v[176:177]
	v_lshlrev_b64 v[22:23], 13, v[22:23]
	v_lshl_add_u64 v[24:25], v[12:13], 0, v[24:25]
	v_lshl_add_u64 v[22:23], v[12:13], 0, v[22:23]
	global_load_dword v84, v[24:25], off
	global_load_dword v85, v[22:23], off
	v_mad_u64_u32 v[104:105], s[24:25], v27, s60, v[4:5]
	v_mad_u64_u32 v[106:107], s[24:25], v26, s60, v[4:5]
	s_add_i32 s24, s22, 12
	s_add_i32 s23, s21, 12
	v_or_b32_e32 v176, s24, v14
	v_mov_b32_e32 v23, v177
	v_or_b32_e32 v26, s23, v1
	v_or_b32_e32 v27, s24, v0
	v_or_b32_e32 v22, s23, v5
	v_lshlrev_b64 v[24:25], 13, v[176:177]
	v_lshlrev_b64 v[22:23], 13, v[22:23]
	v_lshl_add_u64 v[24:25], v[12:13], 0, v[24:25]
	v_lshl_add_u64 v[22:23], v[12:13], 0, v[22:23]
	global_load_dword v86, v[24:25], off
	global_load_dword v87, v[22:23], off
	v_mad_u64_u32 v[108:109], s[24:25], v27, s60, v[4:5]
	v_mad_u64_u32 v[110:111], s[24:25], v26, s60, v[4:5]
	s_add_i32 s24, s22, 16
	s_add_i32 s23, s21, 16
	v_or_b32_e32 v176, s24, v14
	v_mov_b32_e32 v23, v177
	v_or_b32_e32 v26, s23, v1
	v_or_b32_e32 v27, s24, v0
	v_or_b32_e32 v22, s23, v5
	v_lshlrev_b64 v[24:25], 13, v[176:177]
	v_lshlrev_b64 v[22:23], 13, v[22:23]
	v_lshl_add_u64 v[24:25], v[12:13], 0, v[24:25]
	v_lshl_add_u64 v[22:23], v[12:13], 0, v[22:23]
	global_load_dword v88, v[24:25], off
	global_load_dword v89, v[22:23], off
	v_mad_u64_u32 v[112:113], s[24:25], v27, s60, v[4:5]
	v_mad_u64_u32 v[114:115], s[24:25], v26, s60, v[4:5]
	s_add_i32 s24, s22, 20
	s_add_i32 s23, s21, 20
	v_or_b32_e32 v176, s24, v14
	v_mov_b32_e32 v23, v177
	v_or_b32_e32 v26, s23, v1
	v_or_b32_e32 v27, s24, v0
	v_or_b32_e32 v22, s23, v5
	v_lshlrev_b64 v[24:25], 13, v[176:177]
	v_lshlrev_b64 v[22:23], 13, v[22:23]
	v_lshl_add_u64 v[24:25], v[12:13], 0, v[24:25]
	v_lshl_add_u64 v[22:23], v[12:13], 0, v[22:23]
	global_load_dword v90, v[24:25], off
	global_load_dword v91, v[22:23], off
	v_mad_u64_u32 v[116:117], s[24:25], v27, s60, v[4:5]
	v_mad_u64_u32 v[118:119], s[24:25], v26, s60, v[4:5]
	s_add_i32 s24, s22, 24
	s_add_i32 s23, s21, 24
	v_or_b32_e32 v176, s24, v14
	v_mov_b32_e32 v23, v177
	v_or_b32_e32 v26, s23, v1
	v_or_b32_e32 v27, s24, v0
	s_add_i32 s22, s22, 28
	s_add_i32 s21, s21, 28
	s_cmp_lg_u32 s20, 0
	v_or_b32_e32 v22, s23, v5
	v_lshlrev_b64 v[24:25], 13, v[176:177]
	v_lshlrev_b64 v[22:23], 13, v[22:23]
	v_lshl_add_u64 v[24:25], v[12:13], 0, v[24:25]
	v_lshl_add_u64 v[22:23], v[12:13], 0, v[22:23]
	global_load_dword v92, v[24:25], off
	global_load_dword v93, v[22:23], off
	v_mad_u64_u32 v[120:121], s[24:25], v27, s60, v[4:5]
	v_mad_u64_u32 v[122:123], s[24:25], v26, s60, v[4:5]
	v_or_b32_e32 v176, s22, v14
	v_mov_b32_e32 v23, v177
	v_or_b32_e32 v27, s22, v0
	v_or_b32_e32 v26, s21, v1
	v_or_b32_e32 v22, s21, v5
	v_lshlrev_b64 v[24:25], 13, v[176:177]
	v_lshlrev_b64 v[22:23], 13, v[22:23]
	v_lshl_add_u64 v[24:25], v[12:13], 0, v[24:25]
	v_lshl_add_u64 v[22:23], v[12:13], 0, v[22:23]
	global_load_dword v94, v[24:25], off
	global_load_dword v95, v[22:23], off
	v_mad_u64_u32 v[124:125], s[22:23], v27, s60, v[4:5]
	v_mad_u64_u32 v[126:127], s[22:23], v26, s60, v[4:5]
	s_lshl_b32 s22, s19, 1
	s_lshl_b32 s21, s18, 1
	v_or_b32_e32 v176, s22, v14
	v_or_b32_e32 v22, s21, v5
	v_mov_b32_e32 v23, v177
	v_lshlrev_b64 v[24:25], 13, v[176:177]
	v_lshlrev_b64 v[22:23], 13, v[22:23]
	v_lshl_add_u64 v[24:25], v[12:13], 0, v[24:25]
	v_lshl_add_u64 v[22:23], v[12:13], 0, v[22:23]
	global_load_dword v128, v[24:25], off
	global_load_dword v129, v[22:23], off
	v_or_b32_e32 v26, s21, v1
	v_or_b32_e32 v27, s22, v0
	v_mad_u64_u32 v[144:145], s[24:25], v27, s60, v[4:5]
	v_mad_u64_u32 v[146:147], s[24:25], v26, s60, v[4:5]
	s_add_i32 s24, s22, 4
	s_add_i32 s23, s21, 4
	v_or_b32_e32 v176, s24, v14
	v_mov_b32_e32 v23, v177
	v_or_b32_e32 v26, s23, v1
	v_or_b32_e32 v27, s24, v0
	s_add_i32 s19, s19, 16
	s_add_i32 s18, s18, 16
	s_add_i32 s20, s20, -16
	v_or_b32_e32 v22, s23, v5
	v_lshlrev_b64 v[24:25], 13, v[176:177]
	v_lshlrev_b64 v[22:23], 13, v[22:23]
	v_lshl_add_u64 v[24:25], v[12:13], 0, v[24:25]
	v_lshl_add_u64 v[22:23], v[12:13], 0, v[22:23]
	global_load_dword v130, v[24:25], off
	global_load_dword v131, v[22:23], off
	v_mad_u64_u32 v[148:149], s[24:25], v27, s60, v[4:5]
	v_mad_u64_u32 v[150:151], s[24:25], v26, s60, v[4:5]
	s_add_i32 s24, s22, 8
	s_add_i32 s23, s21, 8
; #define LAS __attribute__((address_space(3)))
; __device__ __forceinline__ unsigned pk2(float lo, float hi) { unsigned r; asm("v_cvt_pk_bf16_f32 %0, %1, %2" : "=v"(r) : "v"(lo), "v"(hi)); return r; }
; __device__ __forceinline__ void transpose_item(const float* W, int K, int N, bf16_t* WT, LAS float* scr, int item, int lane, int perm_cols) {
;     ...
;     for (int i = 0; i < 32; ++i) { const int kk = 2 * i + (lane >> 5); scr[kk * 33 + (lane & 31)] = W[(size_t)(k0 + kk) * N + n0 + (lane & 31)]; }
;     asm volatile("s_waitcnt lgkmcnt(0)" ::: "memory");
;     const int c = lane & 7;
; #pragma unroll
;     for (int j = 0; j < 4; ++j) { const int n = (lane >> 3) + 8 * j; const LAS float* s = scr + (8 * c) * 33 + n;
;         u32x4 o; o.x = pk2(s[0 * 33], s[1 * 33]); o.y = pk2(s[2 * 33], s[3 * 33]); o.z = pk2(s[4 * 33], s[5 * 33]); o.w = pk2(s[6 * 33], s[7 * 33]);
;         int rowi = n0 + n;
;         if (rowi < perm_cols) { const int oc = rowi & 255, part = oc >> 6, i6 = oc & 63; rowi = (rowi & ~255) + 128 * (part & 1) + 32 * (2 * (part >> 1) + (i6 >> 5)) + (i6 & 31); }
;         *(u32x4*)(WT + (size_t)rowi * K + k0 + 8 * c) = o; }
;     asm volatile("s_waitcnt lgkmcnt(0)" ::: "memory");
	v_or_b32_e32 v176, s24, v14
	v_mov_b32_e32 v23, v177
	v_or_b32_e32 v26, s23, v1
	v_or_b32_e32 v27, s24, v0
	v_or_b32_e32 v22, s23, v5
	v_lshlrev_b64 v[24:25], 13, v[176:177]
	v_lshlrev_b64 v[22:23], 13, v[22:23]
	v_lshl_add_u64 v[24:25], v[12:13], 0, v[24:25]
	v_lshl_add_u64 v[22:23], v[12:13], 0, v[22:23]
	global_load_dword v132, v[24:25], off
	global_load_dword v133, v[22:23], off
	v_mad_u64_u32 v[152:153], s[24:25], v27, s60, v[4:5]
	v_mad_u64_u32 v[154:155], s[24:25], v26, s60, v[4:5]
	s_add_i32 s24, s22, 12
	s_add_i32 s23, s21, 12
	v_or_b32_e32 v176, s24, v14
	v_mov_b32_e32 v23, v177
	v_or_b32_e32 v26, s23, v1
	v_or_b32_e32 v27, s24, v0
	v_or_b32_e32 v22, s23, v5
	v_lshlrev_b64 v[24:25], 13, v[176:177]
	v_lshlrev_b64 v[22:23], 13, v[22:23]
	v_lshl_add_u64 v[24:25], v[12:13], 0, v[24:25]
	v_lshl_add_u64 v[22:23], v[12:13], 0, v[22:23]
	global_load_dword v134, v[24:25], off
	global_load_dword v135, v[22:23], off
	v_mad_u64_u32 v[156:157], s[24:25], v27, s60, v[4:5]
	v_mad_u64_u32 v[158:159], s[24:25], v26, s60, v[4:5]
	s_add_i32 s24, s22, 16
	s_add_i32 s23, s21, 16
	v_or_b32_e32 v176, s24, v14
	v_mov_b32_e32 v23, v177
	v_or_b32_e32 v26, s23, v1
	v_or_b32_e32 v27, s24, v0
	v_or_b32_e32 v22, s23, v5
	v_lshlrev_b64 v[24:25], 13, v[176:177]
	v_lshlrev_b64 v[22:23], 13, v[22:23]
	v_lshl_add_u64 v[24:25], v[12:13], 0, v[24:25]
	v_lshl_add_u64 v[22:23], v[12:13], 0, v[22:23]
	global_load_dword v136, v[24:25], off
	global_load_dword v137, v[22:23], off
	v_mad_u64_u32 v[160:161], s[24:25], v27, s60, v[4:5]
	v_mad_u64_u32 v[162:163], s[24:25], v26, s60, v[4:5]
	s_add_i32 s24, s22, 20
	s_add_i32 s23, s21, 20
	v_or_b32_e32 v176, s24, v14
	v_mov_b32_e32 v23, v177
	v_or_b32_e32 v26, s23, v1
	v_or_b32_e32 v27, s24, v0
	v_or_b32_e32 v22, s23, v5
	v_lshlrev_b64 v[24:25], 13, v[176:177]
	v_lshlrev_b64 v[22:23], 13, v[22:23]
	v_lshl_add_u64 v[24:25], v[12:13], 0, v[24:25]
	v_lshl_add_u64 v[22:23], v[12:13], 0, v[22:23]
	global_load_dword v138, v[24:25], off
	global_load_dword v139, v[22:23], off
	v_mad_u64_u32 v[164:165], s[24:25], v27, s60, v[4:5]
	v_mad_u64_u32 v[166:167], s[24:25], v26, s60, v[4:5]
	s_add_i32 s24, s22, 24
	s_add_i32 s23, s21, 24
	v_or_b32_e32 v176, s24, v14
	v_mov_b32_e32 v23, v177
	v_or_b32_e32 v26, s23, v1
	v_or_b32_e32 v27, s24, v0
	s_add_i32 s22, s22, 28
	s_add_i32 s21, s21, 28
	s_cmp_lg_u32 s20, 0
	v_or_b32_e32 v22, s23, v5
	v_lshlrev_b64 v[24:25], 13, v[176:177]
	v_lshlrev_b64 v[22:23], 13, v[22:23]
	v_lshl_add_u64 v[24:25], v[12:13], 0, v[24:25]
	v_lshl_add_u64 v[22:23], v[12:13], 0, v[22:23]
	global_load_dword v140, v[24:25], off
	global_load_dword v141, v[22:23], off
	v_mad_u64_u32 v[168:169], s[24:25], v27, s60, v[4:5]
	v_mad_u64_u32 v[170:171], s[24:25], v26, s60, v[4:5]
	v_or_b32_e32 v176, s22, v14
	v_mov_b32_e32 v23, v177
	v_or_b32_e32 v27, s22, v0
	v_or_b32_e32 v26, s21, v1
	v_or_b32_e32 v22, s21, v5
	v_lshlrev_b64 v[24:25], 13, v[176:177]
	v_lshlrev_b64 v[22:23], 13, v[22:23]
	v_lshl_add_u64 v[24:25], v[12:13], 0, v[24:25]
	v_lshl_add_u64 v[22:23], v[12:13], 0, v[22:23]
	global_load_dword v142, v[24:25], off
	global_load_dword v143, v[22:23], off
	v_mad_u64_u32 v[172:173], s[22:23], v27, s60, v[4:5]
	v_mad_u64_u32 v[174:175], s[22:23], v26, s60, v[4:5]
	s_waitcnt vmcnt(31)
	ds_write_b32 v96, v80
	s_waitcnt vmcnt(30)
	ds_write_b32 v98, v81
	s_waitcnt vmcnt(29)
	ds_write_b32 v100, v82
	s_waitcnt vmcnt(28)
	ds_write_b32 v102, v83
	s_waitcnt vmcnt(27)
	ds_write_b32 v104, v84
	s_waitcnt vmcnt(26)
	ds_write_b32 v106, v85
	s_waitcnt vmcnt(25)
	ds_write_b32 v108, v86
	s_waitcnt vmcnt(24)
	ds_write_b32 v110, v87
	s_waitcnt vmcnt(23)
	ds_write_b32 v112, v88
	s_waitcnt vmcnt(22)
	ds_write_b32 v114, v89
	s_waitcnt vmcnt(21)
	ds_write_b32 v116, v90
	s_waitcnt vmcnt(20)
	ds_write_b32 v118, v91
	s_waitcnt vmcnt(19)
	ds_write_b32 v120, v92
	s_waitcnt vmcnt(18)
	ds_write_b32 v122, v93
	s_waitcnt vmcnt(17)
	ds_write_b32 v124, v94
	s_waitcnt vmcnt(16)
	ds_write_b32 v126, v95
	s_waitcnt vmcnt(15)
	ds_write_b32 v144, v128
	s_waitcnt vmcnt(14)
	ds_write_b32 v146, v129
	s_waitcnt vmcnt(13)
	ds_write_b32 v148, v130
	s_waitcnt vmcnt(12)
	ds_write_b32 v150, v131
	s_waitcnt vmcnt(11)
	ds_write_b32 v152, v132
	s_waitcnt vmcnt(10)
	ds_write_b32 v154, v133
	s_waitcnt vmcnt(9)
	ds_write_b32 v156, v134
	s_waitcnt vmcnt(8)
	ds_write_b32 v158, v135
	s_waitcnt vmcnt(7)
	ds_write_b32 v160, v136
	s_waitcnt vmcnt(6)
	ds_write_b32 v162, v137
	s_waitcnt vmcnt(5)
	ds_write_b32 v164, v138
	s_waitcnt vmcnt(4)
	ds_write_b32 v166, v139
	s_waitcnt vmcnt(3)
	ds_write_b32 v168, v140
	s_waitcnt vmcnt(2)
	ds_write_b32 v170, v141
	s_waitcnt vmcnt(1)
	ds_write_b32 v172, v142
	s_waitcnt vmcnt(0)
	ds_write_b32 v174, v143
	s_waitcnt lgkmcnt(0)
	ds_read2_b32 v[26:27], v18 offset0:33 offset1:41
	ds_read2_b32 v[28:29], v18 offset1:8
	ds_read2_b32 v[30:31], v18 offset0:66 offset1:74
	ds_read2_b32 v[32:33], v18 offset0:99 offset1:107
	ds_read2_b32 v[34:35], v18 offset0:132 offset1:140
	ds_read2_b32 v[36:37], v18 offset0:165 offset1:173
	ds_read2_b32 v[38:39], v18 offset0:198 offset1:206
	ds_read2_b32 v[40:41], v18 offset0:231 offset1:239
	s_lshl_b32 s72, s17, 1
	v_or_b32_e32 v5, s16, v17
	v_lshl_add_u64 v[12:13], v[6:7], 0, s[72:73]
	v_lshlrev_b32_e32 v176, 13, v5
	v_or_b32_e32 v5, s16, v19
	s_waitcnt lgkmcnt(6)
	v_cvt_pk_bf16_f32 v22, v28, v26
	v_lshl_add_u64 v[42:43], v[12:13], 0, v[176:177]
	v_lshlrev_b32_e32 v176, 13, v5
	s_waitcnt lgkmcnt(4)
	v_cvt_pk_bf16_f32 v23, v30, v32
	s_waitcnt lgkmcnt(2)
	v_cvt_pk_bf16_f32 v24, v34, v36
	s_waitcnt lgkmcnt(0)
	v_cvt_pk_bf16_f32 v25, v38, v40
	global_store_dwordx4 v[42:43], v[22:25], off
	v_or_b32_e32 v5, s16, v20
	s_nop 0
	v_cvt_pk_bf16_f32 v22, v29, v27
	v_lshl_add_u64 v[26:27], v[12:13], 0, v[176:177]
	v_cvt_pk_bf16_f32 v23, v31, v33
	v_cvt_pk_bf16_f32 v24, v35, v37
	v_cvt_pk_bf16_f32 v25, v39, v41
	global_store_dwordx4 v[26:27], v[22:25], off
	ds_read2_b32 v[26:27], v18 offset0:16 offset1:24
	ds_read2_b32 v[28:29], v18 offset0:49 offset1:57
	ds_read2_b32 v[30:31], v18 offset0:82 offset1:90
	ds_read2_b32 v[32:33], v18 offset0:115 offset1:123
	ds_read2_b32 v[34:35], v18 offset0:148 offset1:156
	ds_read2_b32 v[36:37], v18 offset0:181 offset1:189
	ds_read2_b32 v[38:39], v18 offset0:214 offset1:222
	ds_read2_b32 v[40:41], v18 offset0:247 offset1:255
	v_lshlrev_b32_e32 v176, 13, v5
	v_or_b32_e32 v5, s16, v21
	v_lshl_add_u64 v[42:43], v[12:13], 0, v[176:177]
	v_lshlrev_b32_e32 v176, 13, v5
	s_waitcnt lgkmcnt(6)
	v_cvt_pk_bf16_f32 v22, v26, v28
	s_waitcnt lgkmcnt(4)
	v_cvt_pk_bf16_f32 v23, v30, v32
	s_waitcnt lgkmcnt(2)
	v_cvt_pk_bf16_f32 v24, v34, v36
	s_waitcnt lgkmcnt(0)
	v_cvt_pk_bf16_f32 v25, v38, v40
	v_lshl_add_u64 v[12:13], v[12:13], 0, v[176:177]
	global_store_dwordx4 v[42:43], v[22:25], off
	s_nop 1
	v_cvt_pk_bf16_f32 v22, v27, v29
	v_cvt_pk_bf16_f32 v23, v31, v33
	v_cvt_pk_bf16_f32 v24, v35, v37
	v_cvt_pk_bf16_f32 v25, v39, v41
	global_store_dwordx4 v[12:13], v[22:25], off
	s_waitcnt lgkmcnt(0)
	s_branch .LBB0_579

; #define LAS __attribute__((address_space(3)))
; __device__ __forceinline__ void transpose_item(const float* W, int K, int N, bf16_t* WT, LAS float* scr, int item, int lane, int perm_cols) {
;     const int nblk = N / 32, kb = item / nblk, nb = item % nblk, k0 = 64 * kb, n0 = 32 * nb;
; #pragma unroll 8
;     for (int i = 0; i < 32; ++i) { const int kk = 2 * i + (lane >> 5); scr[kk * 33 + (lane & 31)] = W[(size_t)(k0 + kk) * N + n0 + (lane & 31)]; }
.LBB0_586:
	s_lshl_b32 s21, s18, 1
	s_lshl_b32 s20, s17, 1
	v_or_b32_e32 v22, s21, v14
	v_or_b32_e32 v24, s20, v5
	v_mad_i64_i32 v[22:23], s[22:23], v22, s63, v[12:13]
	v_mad_i64_i32 v[24:25], s[22:23], v24, s63, v[12:13]
	global_load_dword v80, v[22:23], off
	global_load_dword v81, v[24:25], off
	v_or_b32_e32 v26, s20, v1
	v_or_b32_e32 v27, s21, v0
	v_mad_u64_u32 v[96:97], s[22:23], v27, s60, v[4:5]
	v_mad_u64_u32 v[98:99], s[22:23], v26, s60, v[4:5]
	s_add_i32 s23, s21, 4
	s_add_i32 s22, s20, 4
	v_or_b32_e32 v26, s22, v1
	v_or_b32_e32 v27, s23, v0
	s_add_i32 s18, s18, 16
	s_add_i32 s17, s17, 16
	s_add_i32 s19, s19, -16
	v_or_b32_e32 v22, s23, v14
	v_or_b32_e32 v24, s22, v5
	v_mad_i64_i32 v[22:23], s[22:23], v22, s63, v[12:13]
	v_mad_i64_i32 v[24:25], s[22:23], v24, s63, v[12:13]
	global_load_dword v82, v[22:23], off
	global_load_dword v83, v[24:25], off
	v_mad_u64_u32 v[100:101], s[22:23], v27, s60, v[4:5]
	v_mad_u64_u32 v[102:103], s[22:23], v26, s60, v[4:5]
	s_add_i32 s23, s21, 8
	s_add_i32 s22, s20, 8
	v_or_b32_e32 v26, s22, v1
	v_or_b32_e32 v27, s23, v0
	v_or_b32_e32 v22, s23, v14
	v_or_b32_e32 v24, s22, v5
	v_mad_i64_i32 v[22:23], s[22:23], v22, s63, v[12:13]
	v_mad_i64_i32 v[24:25], s[22:23], v24, s63, v[12:13]
	global_load_dword v84, v[22:23], off
	global_load_dword v85, v[24:25], off
	v_mad_u64_u32 v[104:105], s[22:23], v27, s60, v[4:5]
	v_mad_u64_u32 v[106:107], s[22:23], v26, s60, v[4:5]
	s_add_i32 s23, s21, 12
	s_add_i32 s22, s20, 12
	v_or_b32_e32 v26, s22, v1
	v_or_b32_e32 v27, s23, v0
	v_or_b32_e32 v22, s23, v14
	v_or_b32_e32 v24, s22, v5
	v_mad_i64_i32 v[22:23], s[22:23], v22, s63, v[12:13]
	v_mad_i64_i32 v[24:25], s[22:23], v24, s63, v[12:13]
	global_load_dword v86, v[22:23], off
	global_load_dword v87, v[24:25], off
	v_mad_u64_u32 v[108:109], s[22:23], v27, s60, v[4:5]
	v_mad_u64_u32 v[110:111], s[22:23], v26, s60, v[4:5]
	s_add_i32 s23, s21, 16
	s_add_i32 s22, s20, 16
	v_or_b32_e32 v26, s22, v1
	v_or_b32_e32 v27, s23, v0
	v_or_b32_e32 v22, s23, v14
	v_or_b32_e32 v24, s22, v5
	v_mad_i64_i32 v[22:23], s[22:23], v22, s63, v[12:13]
	v_mad_i64_i32 v[24:25], s[22:23], v24, s63, v[12:13]
	global_load_dword v88, v[22:23], off
	global_load_dword v89, v[24:25], off
	v_mad_u64_u32 v[112:113], s[22:23], v27, s60, v[4:5]
	v_mad_u64_u32 v[114:115], s[22:23], v26, s60, v[4:5]
	s_add_i32 s23, s21, 20
	s_add_i32 s22, s20, 20
	v_or_b32_e32 v26, s22, v1
	v_or_b32_e32 v27, s23, v0
	v_or_b32_e32 v22, s23, v14
	v_or_b32_e32 v24, s22, v5
	v_mad_i64_i32 v[22:23], s[22:23], v22, s63, v[12:13]
	v_mad_i64_i32 v[24:25], s[22:23], v24, s63, v[12:13]
	global_load_dword v90, v[22:23], off
	global_load_dword v91, v[24:25], off
	v_mad_u64_u32 v[116:117], s[22:23], v27, s60, v[4:5]
	v_mad_u64_u32 v[118:119], s[22:23], v26, s60, v[4:5]
	s_add_i32 s23, s21, 24
	s_add_i32 s22, s20, 24
	v_or_b32_e32 v26, s22, v1
	v_or_b32_e32 v27, s23, v0
	s_add_i32 s21, s21, 28
	s_add_i32 s20, s20, 28
	s_cmp_lg_u32 s19, 0
	v_or_b32_e32 v22, s23, v14
	v_or_b32_e32 v24, s22, v5
	v_mad_i64_i32 v[22:23], s[22:23], v22, s63, v[12:13]
	v_mad_i64_i32 v[24:25], s[22:23], v24, s63, v[12:13]
	global_load_dword v92, v[22:23], off
	global_load_dword v93, v[24:25], off
	v_mad_u64_u32 v[120:121], s[22:23], v27, s60, v[4:5]
	v_mad_u64_u32 v[122:123], s[22:23], v26, s60, v[4:5]
	v_or_b32_e32 v26, s20, v1
	v_or_b32_e32 v27, s21, v0
	v_or_b32_e32 v22, s21, v14
	v_or_b32_e32 v24, s20, v5
	v_mad_i64_i32 v[22:23], s[20:21], v22, s63, v[12:13]
	v_mad_i64_i32 v[24:25], s[20:21], v24, s63, v[12:13]
	global_load_dword v94, v[22:23], off
	global_load_dword v95, v[24:25], off
	v_mad_u64_u32 v[124:125], s[20:21], v27, s60, v[4:5]
	v_mad_u64_u32 v[126:127], s[20:21], v26, s60, v[4:5]
	s_lshl_b32 s21, s18, 1
	s_lshl_b32 s20, s17, 1
	v_or_b32_e32 v22, s21, v14
	v_or_b32_e32 v24, s20, v5
	v_mad_i64_i32 v[22:23], s[22:23], v22, s63, v[12:13]
	v_mad_i64_i32 v[24:25], s[22:23], v24, s63, v[12:13]
	global_load_dword v128, v[22:23], off
	global_load_dword v129, v[24:25], off
	v_or_b32_e32 v26, s20, v1
	v_or_b32_e32 v27, s21, v0
	v_mad_u64_u32 v[144:145], s[22:23], v27, s60, v[4:5]
	v_mad_u64_u32 v[146:147], s[22:23], v26, s60, v[4:5]
	s_add_i32 s23, s21, 4
	s_add_i32 s22, s20, 4
	v_or_b32_e32 v26, s22, v1
	v_or_b32_e32 v27, s23, v0
	s_add_i32 s18, s18, 16
	s_add_i32 s17, s17, 16
	s_add_i32 s19, s19, -16
	v_or_b32_e32 v22, s23, v14
	v_or_b32_e32 v24, s22, v5
	v_mad_i64_i32 v[22:23], s[22:23], v22, s63, v[12:13]
	v_mad_i64_i32 v[24:25], s[22:23], v24, s63, v[12:13]
	global_load_dword v130, v[22:23], off
	global_load_dword v131, v[24:25], off
	v_mad_u64_u32 v[148:149], s[22:23], v27, s60, v[4:5]
	v_mad_u64_u32 v[150:151], s[22:23], v26, s60, v[4:5]
	s_add_i32 s23, s21, 8
	s_add_i32 s22, s20, 8
	v_or_b32_e32 v26, s22, v1
	v_or_b32_e32 v27, s23, v0
	v_or_b32_e32 v22, s23, v14
	v_or_b32_e32 v24, s22, v5
	v_mad_i64_i32 v[22:23], s[22:23], v22, s63, v[12:13]
	v_mad_i64_i32 v[24:25], s[22:23], v24, s63, v[12:13]
	global_load_dword v132, v[22:23], off
	global_load_dword v133, v[24:25], off
	v_mad_u64_u32 v[152:153], s[22:23], v27, s60, v[4:5]
	v_mad_u64_u32 v[154:155], s[22:23], v26, s60, v[4:5]
	s_add_i32 s23, s21, 12
	s_add_i32 s22, s20, 12
	v_or_b32_e32 v26, s22, v1
	v_or_b32_e32 v27, s23, v0
	v_or_b32_e32 v22, s23, v14
	v_or_b32_e32 v24, s22, v5
	v_mad_i64_i32 v[22:23], s[22:23], v22, s63, v[12:13]
	v_mad_i64_i32 v[24:25], s[22:23], v24, s63, v[12:13]
	global_load_dword v134, v[22:23], off
	global_load_dword v135, v[24:25], off
	v_mad_u64_u32 v[156:157], s[22:23], v27, s60, v[4:5]
	v_mad_u64_u32 v[158:159], s[22:23], v26, s60, v[4:5]
	s_add_i32 s23, s21, 16
	s_add_i32 s22, s20, 16
	v_or_b32_e32 v26, s22, v1
; #define LAS __attribute__((address_space(3)))
; __device__ __forceinline__ unsigned pk2(float lo, float hi) { unsigned r; asm("v_cvt_pk_bf16_f32 %0, %1, %2" : "=v"(r) : "v"(lo), "v"(hi)); return r; }
; __device__ __forceinline__ void transpose_item(const float* W, int K, int N, bf16_t* WT, LAS float* scr, int item, int lane, int perm_cols) {
;     ...
;     for (int i = 0; i < 32; ++i) { const int kk = 2 * i + (lane >> 5); scr[kk * 33 + (lane & 31)] = W[(size_t)(k0 + kk) * N + n0 + (lane & 31)]; }
;     asm volatile("s_waitcnt lgkmcnt(0)" ::: "memory");
;     const int c = lane & 7;
; #pragma unroll
;     for (int j = 0; j < 4; ++j) { const int n = (lane >> 3) + 8 * j; const LAS float* s = scr + (8 * c) * 33 + n;
;         u32x4 o; o.x = pk2(s[0 * 33], s[1 * 33]); o.y = pk2(s[2 * 33], s[3 * 33]); o.z = pk2(s[4 * 33], s[5 * 33]); o.w = pk2(s[6 * 33], s[7 * 33]);
;         int rowi = n0 + n;
;         if (rowi < perm_cols) { const int oc = rowi & 255, part = oc >> 6, i6 = oc & 63; rowi = (rowi & ~255) + 128 * (part & 1) + 32 * (2 * (part >> 1) + (i6 >> 5)) + (i6 & 31); }
;         *(u32x4*)(WT + (size_t)rowi * K + k0 + 8 * c) = o; }
;     asm volatile("s_waitcnt lgkmcnt(0)" ::: "memory");
	v_or_b32_e32 v27, s23, v0
	v_or_b32_e32 v22, s23, v14
	v_or_b32_e32 v24, s22, v5
	v_mad_i64_i32 v[22:23], s[22:23], v22, s63, v[12:13]
	v_mad_i64_i32 v[24:25], s[22:23], v24, s63, v[12:13]
	global_load_dword v136, v[22:23], off
	global_load_dword v137, v[24:25], off
	v_mad_u64_u32 v[160:161], s[22:23], v27, s60, v[4:5]
	v_mad_u64_u32 v[162:163], s[22:23], v26, s60, v[4:5]
	s_add_i32 s23, s21, 20
	s_add_i32 s22, s20, 20
	v_or_b32_e32 v26, s22, v1
	v_or_b32_e32 v27, s23, v0
	v_or_b32_e32 v22, s23, v14
	v_or_b32_e32 v24, s22, v5
	v_mad_i64_i32 v[22:23], s[22:23], v22, s63, v[12:13]
	v_mad_i64_i32 v[24:25], s[22:23], v24, s63, v[12:13]
	global_load_dword v138, v[22:23], off
	global_load_dword v139, v[24:25], off
	v_mad_u64_u32 v[164:165], s[22:23], v27, s60, v[4:5]
	v_mad_u64_u32 v[166:167], s[22:23], v26, s60, v[4:5]
	s_add_i32 s23, s21, 24
	s_add_i32 s22, s20, 24
	v_or_b32_e32 v26, s22, v1
	v_or_b32_e32 v27, s23, v0
	s_add_i32 s21, s21, 28
	s_add_i32 s20, s20, 28
	s_cmp_lg_u32 s19, 0
	v_or_b32_e32 v22, s23, v14
	v_or_b32_e32 v24, s22, v5
	v_mad_i64_i32 v[22:23], s[22:23], v22, s63, v[12:13]
	v_mad_i64_i32 v[24:25], s[22:23], v24, s63, v[12:13]
	global_load_dword v140, v[22:23], off
	global_load_dword v141, v[24:25], off
	v_mad_u64_u32 v[168:169], s[22:23], v27, s60, v[4:5]
	v_mad_u64_u32 v[170:171], s[22:23], v26, s60, v[4:5]
	v_or_b32_e32 v26, s20, v1
	v_or_b32_e32 v27, s21, v0
	v_or_b32_e32 v22, s21, v14
	v_or_b32_e32 v24, s20, v5
	v_mad_i64_i32 v[22:23], s[20:21], v22, s63, v[12:13]
	v_mad_i64_i32 v[24:25], s[20:21], v24, s63, v[12:13]
	global_load_dword v142, v[22:23], off
	global_load_dword v143, v[24:25], off
	v_mad_u64_u32 v[172:173], s[20:21], v27, s60, v[4:5]
	v_mad_u64_u32 v[174:175], s[20:21], v26, s60, v[4:5]
	s_waitcnt vmcnt(31)
	ds_write_b32 v96, v80
	s_waitcnt vmcnt(30)
	ds_write_b32 v98, v81
	s_waitcnt vmcnt(29)
	ds_write_b32 v100, v82
	s_waitcnt vmcnt(28)
	ds_write_b32 v102, v83
	s_waitcnt vmcnt(27)
	ds_write_b32 v104, v84
	s_waitcnt vmcnt(26)
	ds_write_b32 v106, v85
	s_waitcnt vmcnt(25)
	ds_write_b32 v108, v86
	s_waitcnt vmcnt(24)
	ds_write_b32 v110, v87
	s_waitcnt vmcnt(23)
	ds_write_b32 v112, v88
	s_waitcnt vmcnt(22)
	ds_write_b32 v114, v89
	s_waitcnt vmcnt(21)
	ds_write_b32 v116, v90
	s_waitcnt vmcnt(20)
	ds_write_b32 v118, v91
	s_waitcnt vmcnt(19)
	ds_write_b32 v120, v92
	s_waitcnt vmcnt(18)
	ds_write_b32 v122, v93
	s_waitcnt vmcnt(17)
	ds_write_b32 v124, v94
	s_waitcnt vmcnt(16)
	ds_write_b32 v126, v95
	s_waitcnt vmcnt(15)
	ds_write_b32 v144, v128
	s_waitcnt vmcnt(14)
	ds_write_b32 v146, v129
	s_waitcnt vmcnt(13)
	ds_write_b32 v148, v130
	s_waitcnt vmcnt(12)
	ds_write_b32 v150, v131
	s_waitcnt vmcnt(11)
	ds_write_b32 v152, v132
	s_waitcnt vmcnt(10)
	ds_write_b32 v154, v133
	s_waitcnt vmcnt(9)
	ds_write_b32 v156, v134
	s_waitcnt vmcnt(8)
	ds_write_b32 v158, v135
	s_waitcnt vmcnt(7)
	ds_write_b32 v160, v136
	s_waitcnt vmcnt(6)
	ds_write_b32 v162, v137
	s_waitcnt vmcnt(5)
	ds_write_b32 v164, v138
	s_waitcnt vmcnt(4)
	ds_write_b32 v166, v139
	s_waitcnt vmcnt(3)
	ds_write_b32 v168, v140
	s_waitcnt vmcnt(2)
	ds_write_b32 v170, v141
	s_waitcnt vmcnt(1)
	ds_write_b32 v172, v142
	s_waitcnt vmcnt(0)
	ds_write_b32 v174, v143
	s_lshl_b32 s16, s16, 6
	s_and_b32 s16, s16, 0x80
	s_lshr_b32 s17, s40, 1
	s_and_b32 s18, s40, 0xffffff20
	s_waitcnt lgkmcnt(0)
	s_and_b32 s17, s17, 64
	s_or_b32 s16, s18, s16
	s_or_b32 s16, s16, s17
	ds_read2_b32 v[26:27], v18 offset0:33 offset1:41
	ds_read2_b32 v[28:29], v18 offset1:8
	v_or_b32_e32 v5, s40, v17
	ds_read2_b32 v[30:31], v18 offset0:66 offset1:74
	ds_read2_b32 v[32:33], v18 offset0:99 offset1:107
	ds_read2_b32 v[34:35], v18 offset0:132 offset1:140
	ds_read2_b32 v[36:37], v18 offset0:165 offset1:173
	ds_read2_b32 v[38:39], v18 offset0:198 offset1:206
	ds_read2_b32 v[40:41], v18 offset0:231 offset1:239
	v_cmp_gt_i32_e32 vcc, s47, v5
	v_or_b32_e32 v14, s16, v17
	s_ashr_i32 s45, s44, 31
	v_cndmask_b32_e32 v42, v5, v14, vcc
	v_ashrrev_i32_e32 v43, 31, v42
	v_or_b32_e32 v5, s40, v19
	v_lshl_add_u64 v[12:13], s[44:45], 1, v[10:11]
	v_lshlrev_b64 v[42:43], 12, v[42:43]
	v_cmp_gt_i32_e32 vcc, s47, v5
	v_or_b32_e32 v14, s16, v19
	s_waitcnt lgkmcnt(6)
	v_cvt_pk_bf16_f32 v22, v28, v26
	v_lshl_add_u64 v[42:43], v[12:13], 0, v[42:43]
	v_cndmask_b32_e32 v26, v5, v14, vcc
	s_waitcnt lgkmcnt(4)
	v_cvt_pk_bf16_f32 v23, v30, v32
	s_waitcnt lgkmcnt(2)
	v_cvt_pk_bf16_f32 v24, v34, v36
	s_waitcnt lgkmcnt(0)
	v_cvt_pk_bf16_f32 v25, v38, v40
	global_store_dwordx4 v[42:43], v[22:25], off
	v_or_b32_e32 v5, s40, v20
	v_cmp_gt_i32_e32 vcc, s47, v5
	v_cvt_pk_bf16_f32 v22, v29, v27
	v_ashrrev_i32_e32 v27, 31, v26
	v_lshlrev_b64 v[26:27], 12, v[26:27]
	v_lshl_add_u64 v[26:27], v[12:13], 0, v[26:27]
	v_cvt_pk_bf16_f32 v23, v31, v33
	v_cvt_pk_bf16_f32 v24, v35, v37
	v_cvt_pk_bf16_f32 v25, v39, v41
	global_store_dwordx4 v[26:27], v[22:25], off
	ds_read2_b32 v[26:27], v18 offset0:16 offset1:24
	ds_read2_b32 v[28:29], v18 offset0:49 offset1:57
	ds_read2_b32 v[30:31], v18 offset0:82 offset1:90
	ds_read2_b32 v[32:33], v18 offset0:115 offset1:123
	ds_read2_b32 v[34:35], v18 offset0:148 offset1:156
	ds_read2_b32 v[36:37], v18 offset0:181 offset1:189
	ds_read2_b32 v[38:39], v18 offset0:214 offset1:222
	ds_read2_b32 v[40:41], v18 offset0:247 offset1:255
	v_or_b32_e32 v14, s16, v20
	v_cndmask_b32_e32 v42, v5, v14, vcc
	v_ashrrev_i32_e32 v43, 31, v42
	v_or_b32_e32 v5, s40, v21
	v_lshlrev_b64 v[42:43], 12, v[42:43]
	v_cmp_gt_i32_e32 vcc, s47, v5
	v_or_b32_e32 v14, s16, v21
	s_waitcnt lgkmcnt(6)
	v_cvt_pk_bf16_f32 v22, v26, v28
	v_lshl_add_u64 v[42:43], v[12:13], 0, v[42:43]
	v_cndmask_b32_e32 v26, v5, v14, vcc
	s_waitcnt lgkmcnt(4)
	v_cvt_pk_bf16_f32 v23, v30, v32
	s_waitcnt lgkmcnt(2)
	v_cvt_pk_bf16_f32 v24, v34, v36
	s_waitcnt lgkmcnt(0)
	v_cvt_pk_bf16_f32 v25, v38, v40
	global_store_dwordx4 v[42:43], v[22:25], off
	s_nop 1
	v_cvt_pk_bf16_f32 v22, v27, v29
	v_ashrrev_i32_e32 v27, 31, v26
	v_lshlrev_b64 v[26:27], 12, v[26:27]
	v_lshl_add_u64 v[12:13], v[12:13], 0, v[26:27]
	v_cvt_pk_bf16_f32 v23, v31, v33
	v_cvt_pk_bf16_f32 v24, v35, v37
	v_cvt_pk_bf16_f32 v25, v39, v41
	global_store_dwordx4 v[12:13], v[22:25], off
	s_waitcnt lgkmcnt(0)
	s_branch .LBB0_579

; #define LAS __attribute__((address_space(3)))
; __device__ __forceinline__ void transpose_item(const float* W, int K, int N, bf16_t* WT, LAS float* scr, int item, int lane, int perm_cols) {
;     const int nblk = N / 32, kb = item / nblk, nb = item % nblk, k0 = 64 * kb, n0 = 32 * nb;
; #pragma unroll 8
;     for (int i = 0; i < 32; ++i) { const int kk = 2 * i + (lane >> 5); scr[kk * 33 + (lane & 31)] = W[(size_t)(k0 + kk) * N + n0 + (lane & 31)]; }
.LBB0_596:
	s_lshl_b32 s20, s17, 1
	s_lshl_b32 s19, s16, 1
	v_or_b32_e32 v176, s20, v14
	v_or_b32_e32 v20, s19, v5
	v_mov_b32_e32 v21, v177
	v_lshlrev_b64 v[22:23], 13, v[176:177]
	v_lshlrev_b64 v[20:21], 13, v[20:21]
	v_lshl_add_u64 v[22:23], v[12:13], 0, v[22:23]
	v_lshl_add_u64 v[20:21], v[12:13], 0, v[20:21]
	global_load_dword v80, v[22:23], off
	global_load_dword v81, v[20:21], off
	v_or_b32_e32 v24, s19, v1
	v_or_b32_e32 v25, s20, v0
	v_mad_u64_u32 v[96:97], s[22:23], v25, s60, v[4:5]
	v_mad_u64_u32 v[98:99], s[22:23], v24, s60, v[4:5]
	s_add_i32 s22, s20, 4
	s_add_i32 s21, s19, 4
	v_or_b32_e32 v176, s22, v14
	v_mov_b32_e32 v21, v177
	v_or_b32_e32 v24, s21, v1
	v_or_b32_e32 v25, s22, v0
	s_add_i32 s17, s17, 16
	s_add_i32 s16, s16, 16
	s_add_i32 s18, s18, -16
	v_or_b32_e32 v20, s21, v5
	v_lshlrev_b64 v[22:23], 13, v[176:177]
	v_lshlrev_b64 v[20:21], 13, v[20:21]
	v_lshl_add_u64 v[22:23], v[12:13], 0, v[22:23]
	v_lshl_add_u64 v[20:21], v[12:13], 0, v[20:21]
	global_load_dword v82, v[22:23], off
	global_load_dword v83, v[20:21], off
	v_mad_u64_u32 v[100:101], s[22:23], v25, s60, v[4:5]
	v_mad_u64_u32 v[102:103], s[22:23], v24, s60, v[4:5]
	s_add_i32 s22, s20, 8
	s_add_i32 s21, s19, 8
	v_or_b32_e32 v176, s22, v14
	v_mov_b32_e32 v21, v177
	v_or_b32_e32 v24, s21, v1
	v_or_b32_e32 v25, s22, v0
	v_or_b32_e32 v20, s21, v5
	v_lshlrev_b64 v[22:23], 13, v[176:177]
	v_lshlrev_b64 v[20:21], 13, v[20:21]
	v_lshl_add_u64 v[22:23], v[12:13], 0, v[22:23]
	v_lshl_add_u64 v[20:21], v[12:13], 0, v[20:21]
	global_load_dword v84, v[22:23], off
	global_load_dword v85, v[20:21], off
	v_mad_u64_u32 v[104:105], s[22:23], v25, s60, v[4:5]
	v_mad_u64_u32 v[106:107], s[22:23], v24, s60, v[4:5]
	s_add_i32 s22, s20, 12
	s_add_i32 s21, s19, 12
	v_or_b32_e32 v176, s22, v14
	v_mov_b32_e32 v21, v177
	v_or_b32_e32 v24, s21, v1
	v_or_b32_e32 v25, s22, v0
	v_or_b32_e32 v20, s21, v5
	v_lshlrev_b64 v[22:23], 13, v[176:177]
	v_lshlrev_b64 v[20:21], 13, v[20:21]
	v_lshl_add_u64 v[22:23], v[12:13], 0, v[22:23]
	v_lshl_add_u64 v[20:21], v[12:13], 0, v[20:21]
	global_load_dword v86, v[22:23], off
	global_load_dword v87, v[20:21], off
	v_mad_u64_u32 v[108:109], s[22:23], v25, s60, v[4:5]
	v_mad_u64_u32 v[110:111], s[22:23], v24, s60, v[4:5]
	s_add_i32 s22, s20, 16
	s_add_i32 s21, s19, 16
	v_or_b32_e32 v176, s22, v14
	v_mov_b32_e32 v21, v177
	v_or_b32_e32 v24, s21, v1
	v_or_b32_e32 v25, s22, v0
	v_or_b32_e32 v20, s21, v5
	v_lshlrev_b64 v[22:23], 13, v[176:177]
	v_lshlrev_b64 v[20:21], 13, v[20:21]
	v_lshl_add_u64 v[22:23], v[12:13], 0, v[22:23]
	v_lshl_add_u64 v[20:21], v[12:13], 0, v[20:21]
	global_load_dword v88, v[22:23], off
	global_load_dword v89, v[20:21], off
	v_mad_u64_u32 v[112:113], s[22:23], v25, s60, v[4:5]
	v_mad_u64_u32 v[114:115], s[22:23], v24, s60, v[4:5]
	s_add_i32 s22, s20, 20
	s_add_i32 s21, s19, 20
	v_or_b32_e32 v176, s22, v14
	v_mov_b32_e32 v21, v177
	v_or_b32_e32 v24, s21, v1
	v_or_b32_e32 v25, s22, v0
	v_or_b32_e32 v20, s21, v5
	v_lshlrev_b64 v[22:23], 13, v[176:177]
	v_lshlrev_b64 v[20:21], 13, v[20:21]
	v_lshl_add_u64 v[22:23], v[12:13], 0, v[22:23]
	v_lshl_add_u64 v[20:21], v[12:13], 0, v[20:21]
	global_load_dword v90, v[22:23], off
	global_load_dword v91, v[20:21], off
	v_mad_u64_u32 v[116:117], s[22:23], v25, s60, v[4:5]
	v_mad_u64_u32 v[118:119], s[22:23], v24, s60, v[4:5]
	s_add_i32 s22, s20, 24
	s_add_i32 s21, s19, 24
	v_or_b32_e32 v176, s22, v14
	v_mov_b32_e32 v21, v177
	v_or_b32_e32 v24, s21, v1
	v_or_b32_e32 v25, s22, v0
	s_add_i32 s20, s20, 28
	s_add_i32 s19, s19, 28
	s_cmp_lg_u32 s18, 0
	v_or_b32_e32 v20, s21, v5
	v_lshlrev_b64 v[22:23], 13, v[176:177]
	v_lshlrev_b64 v[20:21], 13, v[20:21]
	v_lshl_add_u64 v[22:23], v[12:13], 0, v[22:23]
	v_lshl_add_u64 v[20:21], v[12:13], 0, v[20:21]
	global_load_dword v92, v[22:23], off
	global_load_dword v93, v[20:21], off
	v_mad_u64_u32 v[120:121], s[22:23], v25, s60, v[4:5]
	v_mad_u64_u32 v[122:123], s[22:23], v24, s60, v[4:5]
	v_or_b32_e32 v176, s20, v14
	v_mov_b32_e32 v21, v177
	v_or_b32_e32 v25, s20, v0
	v_or_b32_e32 v24, s19, v1
	v_or_b32_e32 v20, s19, v5
	v_lshlrev_b64 v[22:23], 13, v[176:177]
	v_lshlrev_b64 v[20:21], 13, v[20:21]
	v_lshl_add_u64 v[22:23], v[12:13], 0, v[22:23]
	v_lshl_add_u64 v[20:21], v[12:13], 0, v[20:21]
	global_load_dword v94, v[22:23], off
	global_load_dword v95, v[20:21], off
	v_mad_u64_u32 v[124:125], s[20:21], v25, s60, v[4:5]
	v_mad_u64_u32 v[126:127], s[20:21], v24, s60, v[4:5]
	s_lshl_b32 s20, s17, 1
	s_lshl_b32 s19, s16, 1
	v_or_b32_e32 v176, s20, v14
	v_or_b32_e32 v20, s19, v5
	v_mov_b32_e32 v21, v177
	v_lshlrev_b64 v[22:23], 13, v[176:177]
	v_lshlrev_b64 v[20:21], 13, v[20:21]
	v_lshl_add_u64 v[22:23], v[12:13], 0, v[22:23]
	v_lshl_add_u64 v[20:21], v[12:13], 0, v[20:21]
	global_load_dword v128, v[22:23], off
	global_load_dword v129, v[20:21], off
	v_or_b32_e32 v24, s19, v1
	v_or_b32_e32 v25, s20, v0
	v_mad_u64_u32 v[144:145], s[22:23], v25, s60, v[4:5]
	v_mad_u64_u32 v[146:147], s[22:23], v24, s60, v[4:5]
	s_add_i32 s22, s20, 4
	s_add_i32 s21, s19, 4
	v_or_b32_e32 v176, s22, v14
	v_mov_b32_e32 v21, v177
	v_or_b32_e32 v24, s21, v1
	v_or_b32_e32 v25, s22, v0
	s_add_i32 s17, s17, 16
	s_add_i32 s16, s16, 16
	s_add_i32 s18, s18, -16
	v_or_b32_e32 v20, s21, v5
	v_lshlrev_b64 v[22:23], 13, v[176:177]
	v_lshlrev_b64 v[20:21], 13, v[20:21]
	v_lshl_add_u64 v[22:23], v[12:13], 0, v[22:23]
	v_lshl_add_u64 v[20:21], v[12:13], 0, v[20:21]
	global_load_dword v130, v[22:23], off
	global_load_dword v131, v[20:21], off
	v_mad_u64_u32 v[148:149], s[22:23], v25, s60, v[4:5]
	v_mad_u64_u32 v[150:151], s[22:23], v24, s60, v[4:5]
	s_add_i32 s22, s20, 8
	s_add_i32 s21, s19, 8
; #define LAS __attribute__((address_space(3)))
; __device__ __forceinline__ unsigned pk2(float lo, float hi) { unsigned r; asm("v_cvt_pk_bf16_f32 %0, %1, %2" : "=v"(r) : "v"(lo), "v"(hi)); return r; }
; __device__ __forceinline__ void transpose_item(const float* W, int K, int N, bf16_t* WT, LAS float* scr, int item, int lane, int perm_cols) {
;     ...
;     for (int i = 0; i < 32; ++i) { const int kk = 2 * i + (lane >> 5); scr[kk * 33 + (lane & 31)] = W[(size_t)(k0 + kk) * N + n0 + (lane & 31)]; }
;     asm volatile("s_waitcnt lgkmcnt(0)" ::: "memory");
;     const int c = lane & 7;
; #pragma unroll
;     for (int j = 0; j < 4; ++j) { const int n = (lane >> 3) + 8 * j; const LAS float* s = scr + (8 * c) * 33 + n;
;         u32x4 o; o.x = pk2(s[0 * 33], s[1 * 33]); o.y = pk2(s[2 * 33], s[3 * 33]); o.z = pk2(s[4 * 33], s[5 * 33]); o.w = pk2(s[6 * 33], s[7 * 33]);
;         int rowi = n0 + n;
;         if (rowi < perm_cols) { const int oc = rowi & 255, part = oc >> 6, i6 = oc & 63; rowi = (rowi & ~255) + 128 * (part & 1) + 32 * (2 * (part >> 1) + (i6 >> 5)) + (i6 & 31); }
;         *(u32x4*)(WT + (size_t)rowi * K + k0 + 8 * c) = o; }
;     asm volatile("s_waitcnt lgkmcnt(0)" ::: "memory");
	v_or_b32_e32 v176, s22, v14
	v_mov_b32_e32 v21, v177
	v_or_b32_e32 v24, s21, v1
	v_or_b32_e32 v25, s22, v0
	v_or_b32_e32 v20, s21, v5
	v_lshlrev_b64 v[22:23], 13, v[176:177]
	v_lshlrev_b64 v[20:21], 13, v[20:21]
	v_lshl_add_u64 v[22:23], v[12:13], 0, v[22:23]
	v_lshl_add_u64 v[20:21], v[12:13], 0, v[20:21]
	global_load_dword v132, v[22:23], off
	global_load_dword v133, v[20:21], off
	v_mad_u64_u32 v[152:153], s[22:23], v25, s60, v[4:5]
	v_mad_u64_u32 v[154:155], s[22:23], v24, s60, v[4:5]
	s_add_i32 s22, s20, 12
	s_add_i32 s21, s19, 12
	v_or_b32_e32 v176, s22, v14
	v_mov_b32_e32 v21, v177
	v_or_b32_e32 v24, s21, v1
	v_or_b32_e32 v25, s22, v0
	v_or_b32_e32 v20, s21, v5
	v_lshlrev_b64 v[22:23], 13, v[176:177]
	v_lshlrev_b64 v[20:21], 13, v[20:21]
	v_lshl_add_u64 v[22:23], v[12:13], 0, v[22:23]
	v_lshl_add_u64 v[20:21], v[12:13], 0, v[20:21]
	global_load_dword v134, v[22:23], off
	global_load_dword v135, v[20:21], off
	v_mad_u64_u32 v[156:157], s[22:23], v25, s60, v[4:5]
	v_mad_u64_u32 v[158:159], s[22:23], v24, s60, v[4:5]
	s_add_i32 s22, s20, 16
	s_add_i32 s21, s19, 16
	v_or_b32_e32 v176, s22, v14
	v_mov_b32_e32 v21, v177
	v_or_b32_e32 v24, s21, v1
	v_or_b32_e32 v25, s22, v0
	v_or_b32_e32 v20, s21, v5
	v_lshlrev_b64 v[22:23], 13, v[176:177]
	v_lshlrev_b64 v[20:21], 13, v[20:21]
	v_lshl_add_u64 v[22:23], v[12:13], 0, v[22:23]
	v_lshl_add_u64 v[20:21], v[12:13], 0, v[20:21]
	global_load_dword v136, v[22:23], off
	global_load_dword v137, v[20:21], off
	v_mad_u64_u32 v[160:161], s[22:23], v25, s60, v[4:5]
	v_mad_u64_u32 v[162:163], s[22:23], v24, s60, v[4:5]
	s_add_i32 s22, s20, 20
	s_add_i32 s21, s19, 20
	v_or_b32_e32 v176, s22, v14
	v_mov_b32_e32 v21, v177
	v_or_b32_e32 v24, s21, v1
	v_or_b32_e32 v25, s22, v0
	v_or_b32_e32 v20, s21, v5
	v_lshlrev_b64 v[22:23], 13, v[176:177]
	v_lshlrev_b64 v[20:21], 13, v[20:21]
	v_lshl_add_u64 v[22:23], v[12:13], 0, v[22:23]
	v_lshl_add_u64 v[20:21], v[12:13], 0, v[20:21]
	global_load_dword v138, v[22:23], off
	global_load_dword v139, v[20:21], off
	v_mad_u64_u32 v[164:165], s[22:23], v25, s60, v[4:5]
	v_mad_u64_u32 v[166:167], s[22:23], v24, s60, v[4:5]
	s_add_i32 s22, s20, 24
	s_add_i32 s21, s19, 24
	v_or_b32_e32 v176, s22, v14
	v_mov_b32_e32 v21, v177
	v_or_b32_e32 v24, s21, v1
	v_or_b32_e32 v25, s22, v0
	s_add_i32 s20, s20, 28
	s_add_i32 s19, s19, 28
	s_cmp_lg_u32 s18, 0
	v_or_b32_e32 v20, s21, v5
	v_lshlrev_b64 v[22:23], 13, v[176:177]
	v_lshlrev_b64 v[20:21], 13, v[20:21]
	v_lshl_add_u64 v[22:23], v[12:13], 0, v[22:23]
	v_lshl_add_u64 v[20:21], v[12:13], 0, v[20:21]
	global_load_dword v140, v[22:23], off
	global_load_dword v141, v[20:21], off
	v_mad_u64_u32 v[168:169], s[22:23], v25, s60, v[4:5]
	v_mad_u64_u32 v[170:171], s[22:23], v24, s60, v[4:5]
	v_or_b32_e32 v176, s20, v14
	v_mov_b32_e32 v21, v177
	v_or_b32_e32 v25, s20, v0
	v_or_b32_e32 v24, s19, v1
	v_or_b32_e32 v20, s19, v5
	v_lshlrev_b64 v[22:23], 13, v[176:177]
	v_lshlrev_b64 v[20:21], 13, v[20:21]
	v_lshl_add_u64 v[22:23], v[12:13], 0, v[22:23]
	v_lshl_add_u64 v[20:21], v[12:13], 0, v[20:21]
	global_load_dword v142, v[22:23], off
	global_load_dword v143, v[20:21], off
	v_mad_u64_u32 v[172:173], s[20:21], v25, s60, v[4:5]
	v_mad_u64_u32 v[174:175], s[20:21], v24, s60, v[4:5]
	s_waitcnt vmcnt(31)
	ds_write_b32 v96, v80
	s_waitcnt vmcnt(30)
	ds_write_b32 v98, v81
	s_waitcnt vmcnt(29)
	ds_write_b32 v100, v82
	s_waitcnt vmcnt(28)
	ds_write_b32 v102, v83
	s_waitcnt vmcnt(27)
	ds_write_b32 v104, v84
	s_waitcnt vmcnt(26)
	ds_write_b32 v106, v85
	s_waitcnt vmcnt(25)
	ds_write_b32 v108, v86
	s_waitcnt vmcnt(24)
	ds_write_b32 v110, v87
	s_waitcnt vmcnt(23)
	ds_write_b32 v112, v88
	s_waitcnt vmcnt(22)
	ds_write_b32 v114, v89
	s_waitcnt vmcnt(21)
	ds_write_b32 v116, v90
	s_waitcnt vmcnt(20)
	ds_write_b32 v118, v91
	s_waitcnt vmcnt(19)
	ds_write_b32 v120, v92
	s_waitcnt vmcnt(18)
	ds_write_b32 v122, v93
	s_waitcnt vmcnt(17)
	ds_write_b32 v124, v94
	s_waitcnt vmcnt(16)
	ds_write_b32 v126, v95
	s_waitcnt vmcnt(15)
	ds_write_b32 v144, v128
	s_waitcnt vmcnt(14)
	ds_write_b32 v146, v129
	s_waitcnt vmcnt(13)
	ds_write_b32 v148, v130
	s_waitcnt vmcnt(12)
	ds_write_b32 v150, v131
	s_waitcnt vmcnt(11)
	ds_write_b32 v152, v132
	s_waitcnt vmcnt(10)
	ds_write_b32 v154, v133
	s_waitcnt vmcnt(9)
	ds_write_b32 v156, v134
	s_waitcnt vmcnt(8)
	ds_write_b32 v158, v135
	s_waitcnt vmcnt(7)
	ds_write_b32 v160, v136
	s_waitcnt vmcnt(6)
	ds_write_b32 v162, v137
	s_waitcnt vmcnt(5)
	ds_write_b32 v164, v138
	s_waitcnt vmcnt(4)
	ds_write_b32 v166, v139
	s_waitcnt vmcnt(3)
	ds_write_b32 v168, v140
	s_waitcnt vmcnt(2)
	ds_write_b32 v170, v141
	s_waitcnt vmcnt(1)
	ds_write_b32 v172, v142
	s_waitcnt vmcnt(0)
	ds_write_b32 v174, v143
	s_waitcnt lgkmcnt(0)
	ds_read2_b32 v[24:25], v15 offset0:33 offset1:41
	ds_read2_b32 v[26:27], v15 offset1:8
	ds_read2_b32 v[28:29], v15 offset0:66 offset1:74
	ds_read2_b32 v[30:31], v15 offset0:99 offset1:107
	ds_read2_b32 v[32:33], v15 offset0:132 offset1:140
	ds_read2_b32 v[34:35], v15 offset0:165 offset1:173
	ds_read2_b32 v[36:37], v15 offset0:198 offset1:206
	ds_read2_b32 v[38:39], v15 offset0:231 offset1:239
	s_lshl_b32 s72, s15, 1
	v_or_b32_e32 v5, s14, v16
	v_lshl_add_u64 v[12:13], v[6:7], 0, s[72:73]
	v_lshlrev_b32_e32 v176, 12, v5
	v_or_b32_e32 v5, s14, v17
	s_waitcnt lgkmcnt(6)
	v_cvt_pk_bf16_f32 v20, v26, v24
	v_lshl_add_u64 v[40:41], v[12:13], 0, v[176:177]
	v_lshlrev_b32_e32 v176, 12, v5
	s_waitcnt lgkmcnt(4)
	v_cvt_pk_bf16_f32 v21, v28, v30
	s_waitcnt lgkmcnt(2)
	v_cvt_pk_bf16_f32 v22, v32, v34
	s_waitcnt lgkmcnt(0)
	v_cvt_pk_bf16_f32 v23, v36, v38
	global_store_dwordx4 v[40:41], v[20:23], off
	v_or_b32_e32 v5, s14, v18
	s_nop 0
	v_cvt_pk_bf16_f32 v20, v27, v25
	v_lshl_add_u64 v[24:25], v[12:13], 0, v[176:177]
	v_cvt_pk_bf16_f32 v21, v29, v31
	v_cvt_pk_bf16_f32 v22, v33, v35
	v_cvt_pk_bf16_f32 v23, v37, v39
	global_store_dwordx4 v[24:25], v[20:23], off
	ds_read2_b32 v[24:25], v15 offset0:16 offset1:24
	ds_read2_b32 v[26:27], v15 offset0:49 offset1:57
	ds_read2_b32 v[28:29], v15 offset0:82 offset1:90
	ds_read2_b32 v[30:31], v15 offset0:115 offset1:123
	ds_read2_b32 v[32:33], v15 offset0:148 offset1:156
	ds_read2_b32 v[34:35], v15 offset0:181 offset1:189
	ds_read2_b32 v[36:37], v15 offset0:214 offset1:222
	ds_read2_b32 v[38:39], v15 offset0:247 offset1:255
	v_lshlrev_b32_e32 v176, 12, v5
	v_or_b32_e32 v5, s14, v19
	v_lshl_add_u64 v[40:41], v[12:13], 0, v[176:177]
	v_lshlrev_b32_e32 v176, 12, v5
	s_waitcnt lgkmcnt(6)
	v_cvt_pk_bf16_f32 v20, v24, v26
	s_waitcnt lgkmcnt(4)
	v_cvt_pk_bf16_f32 v21, v28, v30
	s_waitcnt lgkmcnt(2)
	v_cvt_pk_bf16_f32 v22, v32, v34
	s_waitcnt lgkmcnt(0)
	v_cvt_pk_bf16_f32 v23, v36, v38
	v_lshl_add_u64 v[12:13], v[12:13], 0, v[176:177]
	global_store_dwordx4 v[40:41], v[20:23], off
	s_nop 1
	v_cvt_pk_bf16_f32 v20, v25, v27
	v_cvt_pk_bf16_f32 v21, v29, v31
	v_cvt_pk_bf16_f32 v22, v33, v35
	v_cvt_pk_bf16_f32 v23, v37, v39
	global_store_dwordx4 v[12:13], v[20:23], off
	s_waitcnt lgkmcnt(0)
	s_branch .LBB0_592

; #define LAS __attribute__((address_space(3)))
; __device__ __forceinline__ void transpose_item(const float* W, int K, int N, bf16_t* WT, LAS float* scr, int item, int lane, int perm_cols) {
;     const int nblk = N / 32, kb = item / nblk, nb = item % nblk, k0 = 64 * kb, n0 = 32 * nb;
; #pragma unroll 8
;     for (int i = 0; i < 32; ++i) { const int kk = 2 * i + (lane >> 5); scr[kk * 33 + (lane & 31)] = W[(size_t)(k0 + kk) * N + n0 + (lane & 31)]; }
.LBB0_599:
	s_lshl_b32 s19, s16, 1
	s_lshl_b32 s18, s15, 1
	v_or_b32_e32 v20, s19, v14
	v_or_b32_e32 v22, s18, v5
	v_mad_i64_i32 v[20:21], s[20:21], v20, s12, v[12:13]
	v_mad_i64_i32 v[22:23], s[20:21], v22, s12, v[12:13]
	global_load_dword v80, v[20:21], off
	global_load_dword v81, v[22:23], off
	v_or_b32_e32 v24, s18, v1
	v_or_b32_e32 v25, s19, v0
	v_mad_u64_u32 v[96:97], s[20:21], v25, s60, v[4:5]
	v_mad_u64_u32 v[98:99], s[20:21], v24, s60, v[4:5]
	s_add_i32 s21, s19, 4
	s_add_i32 s20, s18, 4
	v_or_b32_e32 v24, s20, v1
	v_or_b32_e32 v25, s21, v0
	s_add_i32 s16, s16, 16
	s_add_i32 s15, s15, 16
	s_add_i32 s17, s17, -16
	v_or_b32_e32 v20, s21, v14
	v_or_b32_e32 v22, s20, v5
	v_mad_i64_i32 v[20:21], s[20:21], v20, s12, v[12:13]
	v_mad_i64_i32 v[22:23], s[20:21], v22, s12, v[12:13]
	global_load_dword v82, v[20:21], off
	global_load_dword v83, v[22:23], off
	v_mad_u64_u32 v[100:101], s[20:21], v25, s60, v[4:5]
	v_mad_u64_u32 v[102:103], s[20:21], v24, s60, v[4:5]
	s_add_i32 s21, s19, 8
	s_add_i32 s20, s18, 8
	v_or_b32_e32 v24, s20, v1
	v_or_b32_e32 v25, s21, v0
	v_or_b32_e32 v20, s21, v14
	v_or_b32_e32 v22, s20, v5
	v_mad_i64_i32 v[20:21], s[20:21], v20, s12, v[12:13]
	v_mad_i64_i32 v[22:23], s[20:21], v22, s12, v[12:13]
	global_load_dword v84, v[20:21], off
	global_load_dword v85, v[22:23], off
	v_mad_u64_u32 v[104:105], s[20:21], v25, s60, v[4:5]
	v_mad_u64_u32 v[106:107], s[20:21], v24, s60, v[4:5]
	s_add_i32 s21, s19, 12
	s_add_i32 s20, s18, 12
	v_or_b32_e32 v24, s20, v1
	v_or_b32_e32 v25, s21, v0
	v_or_b32_e32 v20, s21, v14
	v_or_b32_e32 v22, s20, v5
	v_mad_i64_i32 v[20:21], s[20:21], v20, s12, v[12:13]
	v_mad_i64_i32 v[22:23], s[20:21], v22, s12, v[12:13]
	global_load_dword v86, v[20:21], off
	global_load_dword v87, v[22:23], off
	v_mad_u64_u32 v[108:109], s[20:21], v25, s60, v[4:5]
	v_mad_u64_u32 v[110:111], s[20:21], v24, s60, v[4:5]
	s_add_i32 s21, s19, 16
	s_add_i32 s20, s18, 16
	v_or_b32_e32 v24, s20, v1
	v_or_b32_e32 v25, s21, v0
	v_or_b32_e32 v20, s21, v14
	v_or_b32_e32 v22, s20, v5
	v_mad_i64_i32 v[20:21], s[20:21], v20, s12, v[12:13]
	v_mad_i64_i32 v[22:23], s[20:21], v22, s12, v[12:13]
	global_load_dword v88, v[20:21], off
	global_load_dword v89, v[22:23], off
	v_mad_u64_u32 v[112:113], s[20:21], v25, s60, v[4:5]
	v_mad_u64_u32 v[114:115], s[20:21], v24, s60, v[4:5]
	s_add_i32 s21, s19, 20
	s_add_i32 s20, s18, 20
	v_or_b32_e32 v24, s20, v1
	v_or_b32_e32 v25, s21, v0
	v_or_b32_e32 v20, s21, v14
	v_or_b32_e32 v22, s20, v5
	v_mad_i64_i32 v[20:21], s[20:21], v20, s12, v[12:13]
	v_mad_i64_i32 v[22:23], s[20:21], v22, s12, v[12:13]
	global_load_dword v90, v[20:21], off
	global_load_dword v91, v[22:23], off
	v_mad_u64_u32 v[116:117], s[20:21], v25, s60, v[4:5]
	v_mad_u64_u32 v[118:119], s[20:21], v24, s60, v[4:5]
	s_add_i32 s21, s19, 24
	s_add_i32 s20, s18, 24
	v_or_b32_e32 v24, s20, v1
	v_or_b32_e32 v25, s21, v0
	s_add_i32 s19, s19, 28
	s_add_i32 s18, s18, 28
	s_cmp_lg_u32 s17, 0
	v_or_b32_e32 v20, s21, v14
	v_or_b32_e32 v22, s20, v5
	v_mad_i64_i32 v[20:21], s[20:21], v20, s12, v[12:13]
	v_mad_i64_i32 v[22:23], s[20:21], v22, s12, v[12:13]
	global_load_dword v92, v[20:21], off
	global_load_dword v93, v[22:23], off
	v_mad_u64_u32 v[120:121], s[20:21], v25, s60, v[4:5]
	v_mad_u64_u32 v[122:123], s[20:21], v24, s60, v[4:5]
	v_or_b32_e32 v24, s18, v1
	v_or_b32_e32 v25, s19, v0
	v_or_b32_e32 v20, s19, v14
	v_or_b32_e32 v22, s18, v5
	v_mad_i64_i32 v[20:21], s[18:19], v20, s12, v[12:13]
	v_mad_i64_i32 v[22:23], s[18:19], v22, s12, v[12:13]
	global_load_dword v94, v[20:21], off
	global_load_dword v95, v[22:23], off
	v_mad_u64_u32 v[124:125], s[18:19], v25, s60, v[4:5]
	v_mad_u64_u32 v[126:127], s[18:19], v24, s60, v[4:5]
	s_lshl_b32 s19, s16, 1
	s_lshl_b32 s18, s15, 1
	v_or_b32_e32 v20, s19, v14
	v_or_b32_e32 v22, s18, v5
	v_mad_i64_i32 v[20:21], s[20:21], v20, s12, v[12:13]
	v_mad_i64_i32 v[22:23], s[20:21], v22, s12, v[12:13]
	global_load_dword v128, v[20:21], off
	global_load_dword v129, v[22:23], off
	v_or_b32_e32 v24, s18, v1
	v_or_b32_e32 v25, s19, v0
	v_mad_u64_u32 v[144:145], s[20:21], v25, s60, v[4:5]
	v_mad_u64_u32 v[146:147], s[20:21], v24, s60, v[4:5]
	s_add_i32 s21, s19, 4
	s_add_i32 s20, s18, 4
	v_or_b32_e32 v24, s20, v1
	v_or_b32_e32 v25, s21, v0
	s_add_i32 s16, s16, 16
	s_add_i32 s15, s15, 16
	s_add_i32 s17, s17, -16
	v_or_b32_e32 v20, s21, v14
	v_or_b32_e32 v22, s20, v5
	v_mad_i64_i32 v[20:21], s[20:21], v20, s12, v[12:13]
	v_mad_i64_i32 v[22:23], s[20:21], v22, s12, v[12:13]
	global_load_dword v130, v[20:21], off
	global_load_dword v131, v[22:23], off
	v_mad_u64_u32 v[148:149], s[20:21], v25, s60, v[4:5]
	v_mad_u64_u32 v[150:151], s[20:21], v24, s60, v[4:5]
	s_add_i32 s21, s19, 8
	s_add_i32 s20, s18, 8
	v_or_b32_e32 v24, s20, v1
	v_or_b32_e32 v25, s21, v0
	v_or_b32_e32 v20, s21, v14
	v_or_b32_e32 v22, s20, v5
	v_mad_i64_i32 v[20:21], s[20:21], v20, s12, v[12:13]
	v_mad_i64_i32 v[22:23], s[20:21], v22, s12, v[12:13]
	global_load_dword v132, v[20:21], off
	global_load_dword v133, v[22:23], off
	v_mad_u64_u32 v[152:153], s[20:21], v25, s60, v[4:5]
	v_mad_u64_u32 v[154:155], s[20:21], v24, s60, v[4:5]
	s_add_i32 s21, s19, 12
	s_add_i32 s20, s18, 12
	v_or_b32_e32 v24, s20, v1
	v_or_b32_e32 v25, s21, v0
	v_or_b32_e32 v20, s21, v14
	v_or_b32_e32 v22, s20, v5
	v_mad_i64_i32 v[20:21], s[20:21], v20, s12, v[12:13]
	v_mad_i64_i32 v[22:23], s[20:21], v22, s12, v[12:13]
	global_load_dword v134, v[20:21], off
	global_load_dword v135, v[22:23], off
	v_mad_u64_u32 v[156:157], s[20:21], v25, s60, v[4:5]
	v_mad_u64_u32 v[158:159], s[20:21], v24, s60, v[4:5]
	s_add_i32 s21, s19, 16
	s_add_i32 s20, s18, 16
	v_or_b32_e32 v24, s20, v1
; #define LAS __attribute__((address_space(3)))
; __device__ __forceinline__ unsigned pk2(float lo, float hi) { unsigned r; asm("v_cvt_pk_bf16_f32 %0, %1, %2" : "=v"(r) : "v"(lo), "v"(hi)); return r; }
; __device__ __forceinline__ void transpose_item(const float* W, int K, int N, bf16_t* WT, LAS float* scr, int item, int lane, int perm_cols) {
;     ...
;     for (int i = 0; i < 32; ++i) { const int kk = 2 * i + (lane >> 5); scr[kk * 33 + (lane & 31)] = W[(size_t)(k0 + kk) * N + n0 + (lane & 31)]; }
;     asm volatile("s_waitcnt lgkmcnt(0)" ::: "memory");
;     const int c = lane & 7;
; #pragma unroll
;     for (int j = 0; j < 4; ++j) { const int n = (lane >> 3) + 8 * j; const LAS float* s = scr + (8 * c) * 33 + n;
;         u32x4 o; o.x = pk2(s[0 * 33], s[1 * 33]); o.y = pk2(s[2 * 33], s[3 * 33]); o.z = pk2(s[4 * 33], s[5 * 33]); o.w = pk2(s[6 * 33], s[7 * 33]);
;         int rowi = n0 + n;
;         if (rowi < perm_cols) { const int oc = rowi & 255, part = oc >> 6, i6 = oc & 63; rowi = (rowi & ~255) + 128 * (part & 1) + 32 * (2 * (part >> 1) + (i6 >> 5)) + (i6 & 31); }
;         *(u32x4*)(WT + (size_t)rowi * K + k0 + 8 * c) = o; }
;     asm volatile("s_waitcnt lgkmcnt(0)" ::: "memory");
	v_or_b32_e32 v25, s21, v0
	v_or_b32_e32 v20, s21, v14
	v_or_b32_e32 v22, s20, v5
	v_mad_i64_i32 v[20:21], s[20:21], v20, s12, v[12:13]
	v_mad_i64_i32 v[22:23], s[20:21], v22, s12, v[12:13]
	global_load_dword v136, v[20:21], off
	global_load_dword v137, v[22:23], off
	v_mad_u64_u32 v[160:161], s[20:21], v25, s60, v[4:5]
	v_mad_u64_u32 v[162:163], s[20:21], v24, s60, v[4:5]
	s_add_i32 s21, s19, 20
	s_add_i32 s20, s18, 20
	v_or_b32_e32 v24, s20, v1
	v_or_b32_e32 v25, s21, v0
	v_or_b32_e32 v20, s21, v14
	v_or_b32_e32 v22, s20, v5
	v_mad_i64_i32 v[20:21], s[20:21], v20, s12, v[12:13]
	v_mad_i64_i32 v[22:23], s[20:21], v22, s12, v[12:13]
	global_load_dword v138, v[20:21], off
	global_load_dword v139, v[22:23], off
	v_mad_u64_u32 v[164:165], s[20:21], v25, s60, v[4:5]
	v_mad_u64_u32 v[166:167], s[20:21], v24, s60, v[4:5]
	s_add_i32 s21, s19, 24
	s_add_i32 s20, s18, 24
	v_or_b32_e32 v24, s20, v1
	v_or_b32_e32 v25, s21, v0
	s_add_i32 s19, s19, 28
	s_add_i32 s18, s18, 28
	s_cmp_lg_u32 s17, 0
	v_or_b32_e32 v20, s21, v14
	v_or_b32_e32 v22, s20, v5
	v_mad_i64_i32 v[20:21], s[20:21], v20, s12, v[12:13]
	v_mad_i64_i32 v[22:23], s[20:21], v22, s12, v[12:13]
	global_load_dword v140, v[20:21], off
	global_load_dword v141, v[22:23], off
	v_mad_u64_u32 v[168:169], s[20:21], v25, s60, v[4:5]
	v_mad_u64_u32 v[170:171], s[20:21], v24, s60, v[4:5]
	v_or_b32_e32 v24, s18, v1
	v_or_b32_e32 v25, s19, v0
	v_or_b32_e32 v20, s19, v14
	v_or_b32_e32 v22, s18, v5
	v_mad_i64_i32 v[20:21], s[18:19], v20, s12, v[12:13]
	v_mad_i64_i32 v[22:23], s[18:19], v22, s12, v[12:13]
	global_load_dword v142, v[20:21], off
	global_load_dword v143, v[22:23], off
	v_mad_u64_u32 v[172:173], s[18:19], v25, s60, v[4:5]
	v_mad_u64_u32 v[174:175], s[18:19], v24, s60, v[4:5]
	s_waitcnt vmcnt(31)
	ds_write_b32 v96, v80
	s_waitcnt vmcnt(30)
	ds_write_b32 v98, v81
	s_waitcnt vmcnt(29)
	ds_write_b32 v100, v82
	s_waitcnt vmcnt(28)
	ds_write_b32 v102, v83
	s_waitcnt vmcnt(27)
	ds_write_b32 v104, v84
	s_waitcnt vmcnt(26)
	ds_write_b32 v106, v85
	s_waitcnt vmcnt(25)
	ds_write_b32 v108, v86
	s_waitcnt vmcnt(24)
	ds_write_b32 v110, v87
	s_waitcnt vmcnt(23)
	ds_write_b32 v112, v88
	s_waitcnt vmcnt(22)
	ds_write_b32 v114, v89
	s_waitcnt vmcnt(21)
	ds_write_b32 v116, v90
	s_waitcnt vmcnt(20)
	ds_write_b32 v118, v91
	s_waitcnt vmcnt(19)
	ds_write_b32 v120, v92
	s_waitcnt vmcnt(18)
	ds_write_b32 v122, v93
	s_waitcnt vmcnt(17)
	ds_write_b32 v124, v94
	s_waitcnt vmcnt(16)
	ds_write_b32 v126, v95
	s_waitcnt vmcnt(15)
	ds_write_b32 v144, v128
	s_waitcnt vmcnt(14)
	ds_write_b32 v146, v129
	s_waitcnt vmcnt(13)
	ds_write_b32 v148, v130
	s_waitcnt vmcnt(12)
	ds_write_b32 v150, v131
	s_waitcnt vmcnt(11)
	ds_write_b32 v152, v132
	s_waitcnt vmcnt(10)
	ds_write_b32 v154, v133
	s_waitcnt vmcnt(9)
	ds_write_b32 v156, v134
	s_waitcnt vmcnt(8)
	ds_write_b32 v158, v135
	s_waitcnt vmcnt(7)
	ds_write_b32 v160, v136
	s_waitcnt vmcnt(6)
	ds_write_b32 v162, v137
	s_waitcnt vmcnt(5)
	ds_write_b32 v164, v138
	s_waitcnt vmcnt(4)
	ds_write_b32 v166, v139
	s_waitcnt vmcnt(3)
	ds_write_b32 v168, v140
	s_waitcnt vmcnt(2)
	ds_write_b32 v170, v141
	s_waitcnt vmcnt(1)
	ds_write_b32 v172, v142
	s_waitcnt vmcnt(0)
	ds_write_b32 v174, v143
	s_lshl_b32 s15, s14, 6
	s_and_b32 s15, s15, 0x80
	s_lshr_b32 s16, s36, 1
	s_and_b32 s17, s36, 0xffffff20
	s_and_b32 s16, s16, 64
	s_or_b32 s15, s17, s15
	s_waitcnt lgkmcnt(0)
	s_or_b32 s15, s15, s16
	s_ashr_i32 s39, s38, 31
	ds_read2_b32 v[24:25], v15 offset0:33 offset1:41
	ds_read2_b32 v[26:27], v15 offset1:8
	s_cmp_lt_i32 s14, 0
	ds_read2_b32 v[28:29], v15 offset0:66 offset1:74
	ds_read2_b32 v[30:31], v15 offset0:99 offset1:107
	ds_read2_b32 v[32:33], v15 offset0:132 offset1:140
	ds_read2_b32 v[34:35], v15 offset0:165 offset1:173
	ds_read2_b32 v[36:37], v15 offset0:198 offset1:206
	ds_read2_b32 v[38:39], v15 offset0:231 offset1:239
	s_cselect_b32 s14, s15, s36
	v_or_b32_e32 v40, s14, v16
	v_ashrrev_i32_e32 v41, 31, v40
	v_lshl_add_u64 v[12:13], s[38:39], 1, v[10:11]
	v_lshlrev_b64 v[40:41], 12, v[40:41]
	s_waitcnt lgkmcnt(6)
	v_cvt_pk_bf16_f32 v20, v26, v24
	v_lshl_add_u64 v[40:41], v[12:13], 0, v[40:41]
	v_or_b32_e32 v24, s14, v17
	s_waitcnt lgkmcnt(4)
	v_cvt_pk_bf16_f32 v21, v28, v30
	s_waitcnt lgkmcnt(2)
	v_cvt_pk_bf16_f32 v22, v32, v34
	s_waitcnt lgkmcnt(0)
	v_cvt_pk_bf16_f32 v23, v36, v38
	global_store_dwordx4 v[40:41], v[20:23], off
	v_or_b32_e32 v40, s14, v18
	v_ashrrev_i32_e32 v41, 31, v40
	v_cvt_pk_bf16_f32 v20, v27, v25
	v_ashrrev_i32_e32 v25, 31, v24
	v_lshlrev_b64 v[24:25], 12, v[24:25]
	v_lshl_add_u64 v[24:25], v[12:13], 0, v[24:25]
	v_cvt_pk_bf16_f32 v21, v29, v31
	v_cvt_pk_bf16_f32 v22, v33, v35
	v_cvt_pk_bf16_f32 v23, v37, v39
	global_store_dwordx4 v[24:25], v[20:23], off
	ds_read2_b32 v[24:25], v15 offset0:16 offset1:24
	ds_read2_b32 v[26:27], v15 offset0:49 offset1:57
	ds_read2_b32 v[28:29], v15 offset0:82 offset1:90
	ds_read2_b32 v[30:31], v15 offset0:115 offset1:123
	ds_read2_b32 v[32:33], v15 offset0:148 offset1:156
	ds_read2_b32 v[34:35], v15 offset0:181 offset1:189
	ds_read2_b32 v[36:37], v15 offset0:214 offset1:222
	ds_read2_b32 v[38:39], v15 offset0:247 offset1:255
	v_lshlrev_b64 v[40:41], 12, v[40:41]
	s_waitcnt lgkmcnt(6)
	v_cvt_pk_bf16_f32 v20, v24, v26
	v_lshl_add_u64 v[40:41], v[12:13], 0, v[40:41]
	v_or_b32_e32 v24, s14, v19
	s_waitcnt lgkmcnt(4)
	v_cvt_pk_bf16_f32 v21, v28, v30
	s_waitcnt lgkmcnt(2)
	v_cvt_pk_bf16_f32 v22, v32, v34
	s_waitcnt lgkmcnt(0)
	v_cvt_pk_bf16_f32 v23, v36, v38
	global_store_dwordx4 v[40:41], v[20:23], off
	s_nop 1
	v_cvt_pk_bf16_f32 v20, v25, v27
	v_ashrrev_i32_e32 v25, 31, v24
	v_lshlrev_b64 v[24:25], 12, v[24:25]
	v_lshl_add_u64 v[12:13], v[12:13], 0, v[24:25]
	v_cvt_pk_bf16_f32 v21, v29, v31
	v_cvt_pk_bf16_f32 v22, v33, v35
	v_cvt_pk_bf16_f32 v23, v37, v39
	global_store_dwordx4 v[12:13], v[20:23], off
	s_waitcnt lgkmcnt(0)
	s_branch .LBB0_592
